# GEMM units: first K-loop iteration peeled with zero-initialised MFMA C operands; the 128 accumulator-zeroing moves per unit removed
# speedup vs baseline: 1.0139x; 1.0139x over previous
.LBB0_322:
	s_ashr_i32 s43, s42, 31
	s_lshl_b64 s[46:47], s[42:43], 19
	s_add_u32 s46, s12, s46
	s_addc_u32 s47, s13, s47
	s_and_b64 s[48:49], s[4:5], exec
	s_cselect_b32 s18, s47, s7
	s_cselect_b32 s43, s46, s6
	s_ashr_i32 s45, s44, 31
	s_lshl_b64 s[48:49], s[44:45], 19
	s_add_u32 s48, s59, s48
	s_addc_u32 s49, s60, s49
	s_and_b64 s[50:51], s[4:5], exec
	s_cselect_b32 s45, s49, s9
	s_cselect_b32 s55, s48, s8
	s_add_u32 s6, s6, 0x40080
	s_addc_u32 s7, s7, 0
	s_add_u32 s56, s8, 0x100
	s_addc_u32 s57, s9, 0
	s_mov_b32 s78, -2
	ds_read_b128 v[96:99], v209
	ds_read_b128 v[100:103], v209 offset:1024
	ds_read_b128 v[120:123], v209 offset:2048
	ds_read_b128 v[124:127], v209 offset:3072
	ds_read_b128 v[144:147], v210
	ds_read_b128 v[148:151], v210 offset:1024
	ds_read_b128 v[152:155], v210 offset:2048
	ds_read_b128 v[156:159], v210 offset:3072
	s_add_u32 s8, s6, 0xfffc0080
	s_addc_u32 s9, s7, -1
	s_cmp_eq_u32 s78, 12
	s_cselect_b32 s51, s18, s9
	s_cselect_b32 s50, s43, s8
	s_cselect_b32 s9, s45, s57
	s_cselect_b32 s8, s55, s56
	v_lshl_add_u64 v[206:207], s[6:7], 0, v[170:171]
	s_add_i32 m0, s17, 0xc000
	ds_read_b128 v[178:181], v211
	ds_read_b128 v[182:185], v211 offset:1024
	ds_read_b128 v[186:189], v211 offset:2048
	ds_read_b128 v[190:193], v211 offset:3072
	ds_read_b128 v[194:197], v211 offset:4096
	ds_read_b128 v[198:201], v211 offset:5120
	ds_read_b128 v[202:205], v211 offset:6144
	ds_read_b128 v[218:221], v211 offset:7168
	global_load_lds_dwordx4 v[206:207], off
	v_lshl_add_u64 v[206:207], s[6:7], 0, v[172:173]
	s_add_i32 m0, s17, 0xe000
	s_nop 0
	global_load_lds_dwordx4 v[206:207], off
	s_waitcnt vmcnt(8)
	s_waitcnt lgkmcnt(0)
	s_barrier
	s_setprio 1
	s_waitcnt lgkmcnt(0)
	v_mfma_f32_16x16x32_bf16 v[140:143], v[96:99], v[178:181], 0
	v_mfma_f32_16x16x32_bf16 v[136:139], v[120:123], v[178:181], 0
	v_mfma_f32_16x16x32_bf16 v[116:119], v[96:99], v[186:189], 0
	v_mfma_f32_16x16x32_bf16 v[112:115], v[120:123], v[186:189], 0
	v_mfma_f32_16x16x32_bf16 v[92:95], v[96:99], v[194:197], 0
	v_mfma_f32_16x16x32_bf16 v[88:91], v[120:123], v[194:197], 0
	v_mfma_f32_16x16x32_bf16 v[76:79], v[96:99], v[202:205], 0
	v_mfma_f32_16x16x32_bf16 v[72:75], v[120:123], v[202:205], 0
	v_mfma_f32_16x16x32_bf16 v[140:143], v[100:103], v[182:185], v[140:143]
	v_mfma_f32_16x16x32_bf16 v[136:139], v[124:127], v[182:185], v[136:139]
	v_mfma_f32_16x16x32_bf16 v[116:119], v[100:103], v[190:193], v[116:119]
	v_mfma_f32_16x16x32_bf16 v[112:115], v[124:127], v[190:193], v[112:115]
	v_mfma_f32_16x16x32_bf16 v[92:95], v[100:103], v[198:201], v[92:95]
	v_mfma_f32_16x16x32_bf16 v[88:91], v[124:127], v[198:201], v[88:91]
	v_mfma_f32_16x16x32_bf16 v[76:79], v[100:103], v[218:221], v[76:79]
	v_mfma_f32_16x16x32_bf16 v[72:75], v[124:127], v[218:221], v[72:75]
	s_setprio 0
	s_setprio 1
	v_mfma_f32_16x16x32_bf16 v[132:135], v[144:147], v[178:181], 0
	v_mfma_f32_16x16x32_bf16 v[128:131], v[152:155], v[178:181], 0
	v_mfma_f32_16x16x32_bf16 v[108:111], v[144:147], v[186:189], 0
	v_mfma_f32_16x16x32_bf16 v[104:107], v[152:155], v[186:189], 0
	v_mfma_f32_16x16x32_bf16 v[84:87], v[144:147], v[194:197], 0
	v_mfma_f32_16x16x32_bf16 v[80:83], v[152:155], v[194:197], 0
	v_mfma_f32_16x16x32_bf16 v[68:71], v[144:147], v[202:205], 0
	v_mfma_f32_16x16x32_bf16 v[64:67], v[152:155], v[202:205], 0
	v_mfma_f32_16x16x32_bf16 v[132:135], v[148:151], v[182:185], v[132:135]
	v_mfma_f32_16x16x32_bf16 v[128:131], v[156:159], v[182:185], v[128:131]
	v_mfma_f32_16x16x32_bf16 v[108:111], v[148:151], v[190:193], v[108:111]
	v_mfma_f32_16x16x32_bf16 v[104:107], v[156:159], v[190:193], v[104:107]
	s_setprio 2
	s_barrier
	v_mfma_f32_16x16x32_bf16 v[84:87], v[148:151], v[198:201], v[84:87]
	v_mfma_f32_16x16x32_bf16 v[80:83], v[156:159], v[198:201], v[80:83]
	v_mfma_f32_16x16x32_bf16 v[68:71], v[148:151], v[218:221], v[68:71]
	v_mfma_f32_16x16x32_bf16 v[64:67], v[156:159], v[218:221], v[64:67]
	s_setprio 0
	s_add_i32 s79, s73, s61
	v_lshl_add_u64 v[206:207], s[8:9], 0, v[162:163]
	s_mov_b32 m0, s79
	ds_read_b128 v[178:181], v211 offset:16384
	ds_read_b128 v[182:185], v211 offset:17408
	ds_read_b128 v[186:189], v211 offset:18432
	ds_read_b128 v[190:193], v211 offset:19456
	ds_read_b128 v[194:197], v211 offset:20480
	ds_read_b128 v[198:201], v211 offset:21504
	ds_read_b128 v[202:205], v211 offset:22528
	ds_read_b128 v[218:221], v211 offset:23552
	global_load_lds_dwordx4 v[206:207], off
	s_add_i32 m0, s79, 0x2000
	s_add_u32 s80, s8, 0x40000
	v_lshl_add_u64 v[222:223], s[8:9], 0, v[166:167]
	s_addc_u32 s81, s9, 0
	s_add_i32 s79, s74, s61
	global_load_lds_dwordx4 v[222:223], off
	v_lshl_add_u64 v[224:225], s[80:81], 0, v[162:163]
	s_mov_b32 m0, s79
	v_lshl_add_u64 v[226:227], s[50:51], 0, v[164:165]
	global_load_lds_dwordx4 v[224:225], off
	v_lshl_add_u64 v[224:225], s[80:81], 0, v[166:167]
	s_add_i32 m0, s79, 0x2000
	s_nop 0
	global_load_lds_dwordx4 v[224:225], off
	v_lshl_add_u64 v[224:225], s[50:51], 0, v[160:161]
	s_mov_b32 m0, s17
	s_nop 0
	global_load_lds_dwordx4 v[224:225], off
	s_mov_b32 m0, s62
	s_nop 0
	global_load_lds_dwordx4 v[226:227], off
	s_waitcnt vmcnt(8)
	s_waitcnt lgkmcnt(0)
	s_barrier
	s_setprio 1
	s_waitcnt lgkmcnt(0)
	v_mfma_f32_16x16x32_bf16 v[60:63], v[96:99], v[178:181], 0
	v_mfma_f32_16x16x32_bf16 v[56:59], v[120:123], v[178:181], 0
	v_mfma_f32_16x16x32_bf16 v[44:47], v[96:99], v[186:189], 0
	v_mfma_f32_16x16x32_bf16 v[40:43], v[120:123], v[186:189], 0
	v_mfma_f32_16x16x32_bf16 v[28:31], v[96:99], v[194:197], 0
	v_mfma_f32_16x16x32_bf16 v[24:27], v[120:123], v[194:197], 0
	v_mfma_f32_16x16x32_bf16 v[12:15], v[96:99], v[202:205], 0
	v_mfma_f32_16x16x32_bf16 v[8:11], v[120:123], v[202:205], 0
	v_mfma_f32_16x16x32_bf16 v[60:63], v[100:103], v[182:185], v[60:63]
	v_mfma_f32_16x16x32_bf16 v[56:59], v[124:127], v[182:185], v[56:59]
	v_mfma_f32_16x16x32_bf16 v[44:47], v[100:103], v[190:193], v[44:47]
	v_mfma_f32_16x16x32_bf16 v[40:43], v[124:127], v[190:193], v[40:43]
	v_mfma_f32_16x16x32_bf16 v[28:31], v[100:103], v[198:201], v[28:31]
	v_mfma_f32_16x16x32_bf16 v[24:27], v[124:127], v[198:201], v[24:27]
	v_mfma_f32_16x16x32_bf16 v[12:15], v[100:103], v[218:221], v[12:15]
	v_mfma_f32_16x16x32_bf16 v[8:11], v[124:127], v[218:221], v[8:11]
	s_setprio 0
	s_setprio 1
	v_mfma_f32_16x16x32_bf16 v[52:55], v[144:147], v[178:181], 0
	v_mfma_f32_16x16x32_bf16 v[48:51], v[152:155], v[178:181], 0
	v_mfma_f32_16x16x32_bf16 v[36:39], v[144:147], v[186:189], 0
	v_mfma_f32_16x16x32_bf16 v[32:35], v[152:155], v[186:189], 0
	v_mfma_f32_16x16x32_bf16 v[20:23], v[144:147], v[194:197], 0
	v_mfma_f32_16x16x32_bf16 v[16:19], v[152:155], v[194:197], 0
	v_mfma_f32_16x16x32_bf16 v[4:7], v[144:147], v[202:205], 0
	v_mfma_f32_16x16x32_bf16 v[0:3], v[152:155], v[202:205], 0
	v_mfma_f32_16x16x32_bf16 v[52:55], v[148:151], v[182:185], v[52:55]
	v_mfma_f32_16x16x32_bf16 v[48:51], v[156:159], v[182:185], v[48:51]
	v_mfma_f32_16x16x32_bf16 v[36:39], v[148:151], v[190:193], v[36:39]
	v_mfma_f32_16x16x32_bf16 v[32:35], v[156:159], v[190:193], v[32:35]
	s_setprio 2
	s_barrier
	v_mfma_f32_16x16x32_bf16 v[20:23], v[148:151], v[198:201], v[20:23]
	v_mfma_f32_16x16x32_bf16 v[16:19], v[156:159], v[198:201], v[16:19]
	v_mfma_f32_16x16x32_bf16 v[4:7], v[148:151], v[218:221], v[4:7]
	v_mfma_f32_16x16x32_bf16 v[0:3], v[156:159], v[218:221], v[0:3]
	s_setprio 0
	s_add_i32 s79, 0, 0x18000
	s_add_i32 s80, 0, 0x1c000
	v_add_u32_e32 v124, s79, v208
	v_add_u32_e32 v156, s80, v208
	ds_read_b128 v[96:99], v124
	ds_read_b128 v[100:103], v124 offset:1024
	ds_read_b128 v[120:123], v124 offset:2048
	ds_read_b128 v[124:127], v124 offset:3072
	ds_read_b128 v[144:147], v156
	ds_read_b128 v[148:151], v156 offset:1024
	ds_read_b128 v[152:155], v156 offset:2048
	ds_read_b128 v[156:159], v156 offset:3072
	s_add_u32 s50, s50, 0x40000
	s_addc_u32 s51, s51, 0
	s_mov_b32 m0, s63
	v_lshl_add_u64 v[228:229], s[50:51], 0, v[160:161]
	ds_read_b128 v[178:181], v211 offset:32768
	ds_read_b128 v[182:185], v211 offset:33792
	ds_read_b128 v[186:189], v211 offset:34816
	ds_read_b128 v[190:193], v211 offset:35840
	ds_read_b128 v[194:197], v211 offset:36864
	ds_read_b128 v[198:201], v211 offset:37888
	ds_read_b128 v[202:205], v211 offset:38912
	ds_read_b128 v[218:221], v211 offset:39936
	global_load_lds_dwordx4 v[228:229], off
	v_lshl_add_u64 v[228:229], s[50:51], 0, v[164:165]
	s_mov_b32 m0, s64
	s_nop 0
	global_load_lds_dwordx4 v[228:229], off
	s_waitcnt vmcnt(8)
	s_waitcnt lgkmcnt(0)
	s_barrier
	s_setprio 1
	s_waitcnt lgkmcnt(0)
	v_mfma_f32_16x16x32_bf16 v[140:143], v[96:99], v[178:181], v[140:143]
	v_mfma_f32_16x16x32_bf16 v[136:139], v[120:123], v[178:181], v[136:139]
	v_mfma_f32_16x16x32_bf16 v[116:119], v[96:99], v[186:189], v[116:119]
	v_mfma_f32_16x16x32_bf16 v[112:115], v[120:123], v[186:189], v[112:115]
	v_mfma_f32_16x16x32_bf16 v[92:95], v[96:99], v[194:197], v[92:95]
	v_mfma_f32_16x16x32_bf16 v[88:91], v[120:123], v[194:197], v[88:91]
	v_mfma_f32_16x16x32_bf16 v[76:79], v[96:99], v[202:205], v[76:79]
	v_mfma_f32_16x16x32_bf16 v[72:75], v[120:123], v[202:205], v[72:75]
	v_mfma_f32_16x16x32_bf16 v[140:143], v[100:103], v[182:185], v[140:143]
	v_mfma_f32_16x16x32_bf16 v[136:139], v[124:127], v[182:185], v[136:139]
	v_mfma_f32_16x16x32_bf16 v[116:119], v[100:103], v[190:193], v[116:119]
	v_mfma_f32_16x16x32_bf16 v[112:115], v[124:127], v[190:193], v[112:115]
	v_mfma_f32_16x16x32_bf16 v[92:95], v[100:103], v[198:201], v[92:95]
	v_mfma_f32_16x16x32_bf16 v[88:91], v[124:127], v[198:201], v[88:91]
	v_mfma_f32_16x16x32_bf16 v[76:79], v[100:103], v[218:221], v[76:79]
	v_mfma_f32_16x16x32_bf16 v[72:75], v[124:127], v[218:221], v[72:75]
	s_setprio 0
	s_setprio 1
	v_mfma_f32_16x16x32_bf16 v[132:135], v[144:147], v[178:181], v[132:135]
	v_mfma_f32_16x16x32_bf16 v[128:131], v[152:155], v[178:181], v[128:131]
	v_mfma_f32_16x16x32_bf16 v[108:111], v[144:147], v[186:189], v[108:111]
	v_mfma_f32_16x16x32_bf16 v[104:107], v[152:155], v[186:189], v[104:107]
	v_mfma_f32_16x16x32_bf16 v[84:87], v[144:147], v[194:197], v[84:87]
	v_mfma_f32_16x16x32_bf16 v[80:83], v[152:155], v[194:197], v[80:83]
	v_mfma_f32_16x16x32_bf16 v[68:71], v[144:147], v[202:205], v[68:71]
	v_mfma_f32_16x16x32_bf16 v[64:67], v[152:155], v[202:205], v[64:67]
	v_mfma_f32_16x16x32_bf16 v[132:135], v[148:151], v[182:185], v[132:135]
	v_mfma_f32_16x16x32_bf16 v[128:131], v[156:159], v[182:185], v[128:131]
	v_mfma_f32_16x16x32_bf16 v[108:111], v[148:151], v[190:193], v[108:111]
	v_mfma_f32_16x16x32_bf16 v[104:107], v[156:159], v[190:193], v[104:107]
	s_setprio 2
	s_barrier
	v_mfma_f32_16x16x32_bf16 v[84:87], v[148:151], v[198:201], v[84:87]
	v_mfma_f32_16x16x32_bf16 v[80:83], v[156:159], v[198:201], v[80:83]
	v_mfma_f32_16x16x32_bf16 v[68:71], v[148:151], v[218:221], v[68:71]
	v_mfma_f32_16x16x32_bf16 v[64:67], v[156:159], v[218:221], v[64:67]
	s_setprio 0
	s_add_i32 s50, s79, s61
	v_lshl_add_u64 v[206:207], v[206:207], 0, s[36:37]
	s_mov_b32 m0, s50
	ds_read_b128 v[178:181], v211 offset:49152
	ds_read_b128 v[182:185], v211 offset:50176
	ds_read_b128 v[186:189], v211 offset:51200
	ds_read_b128 v[190:193], v211 offset:52224
	ds_read_b128 v[194:197], v211 offset:53248
	ds_read_b128 v[198:201], v211 offset:54272
	ds_read_b128 v[202:205], v211 offset:55296
	ds_read_b128 v[218:221], v211 offset:56320
	global_load_lds_dwordx4 v[206:207], off
	s_add_i32 m0, s50, 0x2000
	s_add_u32 s8, s8, 0x40080
	v_lshl_add_u64 v[206:207], v[222:223], 0, s[36:37]
	s_addc_u32 s9, s9, 0
	s_add_i32 s50, s80, s61
	global_load_lds_dwordx4 v[206:207], off
	v_lshl_add_u64 v[206:207], s[8:9], 0, v[162:163]
	s_mov_b32 m0, s50
	s_nop 0
	global_load_lds_dwordx4 v[206:207], off
	v_lshl_add_u64 v[206:207], s[8:9], 0, v[166:167]
	s_add_i32 m0, s50, 0x2000
	s_nop 0
	global_load_lds_dwordx4 v[206:207], off
	v_lshl_add_u64 v[206:207], v[224:225], 0, s[36:37]
	s_mov_b32 m0, s68
	s_nop 0
	global_load_lds_dwordx4 v[206:207], off
	v_lshl_add_u64 v[206:207], v[226:227], 0, s[36:37]
	s_mov_b32 m0, s69
	s_nop 0
	global_load_lds_dwordx4 v[206:207], off
	s_waitcnt vmcnt(8)
	s_waitcnt lgkmcnt(0)
	s_barrier
	s_setprio 1
	s_waitcnt lgkmcnt(0)
	v_mfma_f32_16x16x32_bf16 v[60:63], v[96:99], v[178:181], v[60:63]
	v_mfma_f32_16x16x32_bf16 v[56:59], v[120:123], v[178:181], v[56:59]
	v_mfma_f32_16x16x32_bf16 v[44:47], v[96:99], v[186:189], v[44:47]
	v_mfma_f32_16x16x32_bf16 v[40:43], v[120:123], v[186:189], v[40:43]
	v_mfma_f32_16x16x32_bf16 v[28:31], v[96:99], v[194:197], v[28:31]
	v_mfma_f32_16x16x32_bf16 v[24:27], v[120:123], v[194:197], v[24:27]
	v_mfma_f32_16x16x32_bf16 v[12:15], v[96:99], v[202:205], v[12:15]
	v_mfma_f32_16x16x32_bf16 v[8:11], v[120:123], v[202:205], v[8:11]
	v_mfma_f32_16x16x32_bf16 v[60:63], v[100:103], v[182:185], v[60:63]
	v_mfma_f32_16x16x32_bf16 v[56:59], v[124:127], v[182:185], v[56:59]
	v_mfma_f32_16x16x32_bf16 v[44:47], v[100:103], v[190:193], v[44:47]
	v_mfma_f32_16x16x32_bf16 v[40:43], v[124:127], v[190:193], v[40:43]
	v_mfma_f32_16x16x32_bf16 v[28:31], v[100:103], v[198:201], v[28:31]
	v_mfma_f32_16x16x32_bf16 v[24:27], v[124:127], v[198:201], v[24:27]
	v_mfma_f32_16x16x32_bf16 v[12:15], v[100:103], v[218:221], v[12:15]
	v_mfma_f32_16x16x32_bf16 v[8:11], v[124:127], v[218:221], v[8:11]
	s_setprio 0
	s_setprio 1
	v_mfma_f32_16x16x32_bf16 v[52:55], v[144:147], v[178:181], v[52:55]
	v_mfma_f32_16x16x32_bf16 v[48:51], v[152:155], v[178:181], v[48:51]
	v_mfma_f32_16x16x32_bf16 v[36:39], v[144:147], v[186:189], v[36:39]
	v_mfma_f32_16x16x32_bf16 v[32:35], v[152:155], v[186:189], v[32:35]
	v_mfma_f32_16x16x32_bf16 v[20:23], v[144:147], v[194:197], v[20:23]
	v_mfma_f32_16x16x32_bf16 v[16:19], v[152:155], v[194:197], v[16:19]
	v_mfma_f32_16x16x32_bf16 v[4:7], v[144:147], v[202:205], v[4:7]
	v_mfma_f32_16x16x32_bf16 v[0:3], v[152:155], v[202:205], v[0:3]
	v_mfma_f32_16x16x32_bf16 v[52:55], v[148:151], v[182:185], v[52:55]
	v_mfma_f32_16x16x32_bf16 v[48:51], v[156:159], v[182:185], v[48:51]
	v_mfma_f32_16x16x32_bf16 v[36:39], v[148:151], v[190:193], v[36:39]
	v_mfma_f32_16x16x32_bf16 v[32:35], v[156:159], v[190:193], v[32:35]
	s_setprio 2
	s_barrier
	v_mfma_f32_16x16x32_bf16 v[20:23], v[148:151], v[198:201], v[20:23]
	v_mfma_f32_16x16x32_bf16 v[16:19], v[156:159], v[198:201], v[16:19]
	v_mfma_f32_16x16x32_bf16 v[4:7], v[148:151], v[218:221], v[4:7]
	v_mfma_f32_16x16x32_bf16 v[0:3], v[156:159], v[218:221], v[0:3]
	s_setprio 0
	s_add_i32 s78, s78, 2
	s_add_u32 s6, s6, 0x100
	s_addc_u32 s7, s7, 0
	s_add_u32 s56, s56, 0x100
	s_addc_u32 s57, s57, 0
	s_cmp_gt_u32 s78, 13

.LBB0_783:
	s_ashr_i32 s23, s22, 31
	s_lshl_b64 s[26:27], s[22:23], 19
	s_add_u32 s26, s43, s26
	s_addc_u32 s27, s44, s27
	s_and_b64 s[28:29], s[4:5], exec
	s_cselect_b32 s23, s27, s37
	s_cselect_b32 s31, s26, s36
	s_ashr_i32 s25, s24, 31
	s_lshl_b64 s[28:29], s[24:25], 19
	s_add_u32 s28, s45, s28
	s_addc_u32 s29, s46, s29
	s_and_b64 s[40:41], s[4:5], exec
	s_cselect_b32 s25, s29, s39
	s_cselect_b32 s62, s28, s38
	s_add_u32 s36, s36, 0x40080
	s_addc_u32 s37, s37, 0
	s_add_u32 s63, s38, 0x100
	s_addc_u32 s64, s39, 0
	s_mov_b32 s65, -2
	ds_read_b128 v[144:147], v163
	ds_read_b128 v[148:151], v163 offset:1024
	ds_read_b128 v[152:155], v163 offset:2048
	ds_read_b128 v[156:159], v163 offset:3072
	ds_read_b128 v[168:171], v164
	ds_read_b128 v[172:175], v164 offset:1024
	ds_read_b128 v[176:179], v164 offset:2048
	ds_read_b128 v[180:183], v164 offset:3072
	s_add_u32 s38, s36, 0xfffc0080
	s_addc_u32 s39, s37, -1
	s_cmp_eq_u32 s65, 12
	s_cselect_b32 s41, s23, s39
	s_cselect_b32 s40, s31, s38
	s_cselect_b32 s39, s25, s64
	s_cselect_b32 s38, s62, s63
	v_lshl_add_u64 v[160:161], s[36:37], 0, v[136:137]
	s_add_i32 m0, s50, 0xc000
	ds_read_b128 v[184:187], v165
	ds_read_b128 v[188:191], v165 offset:1024
	ds_read_b128 v[192:195], v165 offset:2048
	ds_read_b128 v[196:199], v165 offset:3072
	ds_read_b128 v[200:203], v165 offset:4096
	ds_read_b128 v[204:207], v165 offset:5120
	ds_read_b128 v[208:211], v165 offset:6144
	ds_read_b128 v[212:215], v165 offset:7168
	global_load_lds_dwordx4 v[160:161], off
	v_lshl_add_u64 v[160:161], s[36:37], 0, v[138:139]
	s_add_i32 m0, s50, 0xe000
	s_nop 0
	global_load_lds_dwordx4 v[160:161], off
	s_waitcnt vmcnt(8)
	s_waitcnt lgkmcnt(0)
	s_barrier
	s_setprio 1
	s_waitcnt lgkmcnt(0)
	v_mfma_f32_16x16x32_bf16 v[124:127], v[144:147], v[184:187], 0
	v_mfma_f32_16x16x32_bf16 v[120:123], v[152:155], v[184:187], 0
	v_mfma_f32_16x16x32_bf16 v[108:111], v[144:147], v[192:195], 0
	v_mfma_f32_16x16x32_bf16 v[104:107], v[152:155], v[192:195], 0
	v_mfma_f32_16x16x32_bf16 v[92:95], v[144:147], v[200:203], 0
	v_mfma_f32_16x16x32_bf16 v[88:91], v[152:155], v[200:203], 0
	v_mfma_f32_16x16x32_bf16 v[76:79], v[144:147], v[208:211], 0
	v_mfma_f32_16x16x32_bf16 v[72:75], v[152:155], v[208:211], 0
	v_mfma_f32_16x16x32_bf16 v[124:127], v[148:151], v[188:191], v[124:127]
	v_mfma_f32_16x16x32_bf16 v[120:123], v[156:159], v[188:191], v[120:123]
	v_mfma_f32_16x16x32_bf16 v[108:111], v[148:151], v[196:199], v[108:111]
	v_mfma_f32_16x16x32_bf16 v[104:107], v[156:159], v[196:199], v[104:107]
	v_mfma_f32_16x16x32_bf16 v[92:95], v[148:151], v[204:207], v[92:95]
	v_mfma_f32_16x16x32_bf16 v[88:91], v[156:159], v[204:207], v[88:91]
	v_mfma_f32_16x16x32_bf16 v[76:79], v[148:151], v[212:215], v[76:79]
	v_mfma_f32_16x16x32_bf16 v[72:75], v[156:159], v[212:215], v[72:75]
	s_setprio 0
	s_setprio 1
	v_mfma_f32_16x16x32_bf16 v[116:119], v[168:171], v[184:187], 0
	v_mfma_f32_16x16x32_bf16 v[112:115], v[176:179], v[184:187], 0
	v_mfma_f32_16x16x32_bf16 v[100:103], v[168:171], v[192:195], 0
	v_mfma_f32_16x16x32_bf16 v[96:99], v[176:179], v[192:195], 0
	v_mfma_f32_16x16x32_bf16 v[84:87], v[168:171], v[200:203], 0
	v_mfma_f32_16x16x32_bf16 v[80:83], v[176:179], v[200:203], 0
	v_mfma_f32_16x16x32_bf16 v[68:71], v[168:171], v[208:211], 0
	v_mfma_f32_16x16x32_bf16 v[64:67], v[176:179], v[208:211], 0
	v_mfma_f32_16x16x32_bf16 v[116:119], v[172:175], v[188:191], v[116:119]
	v_mfma_f32_16x16x32_bf16 v[112:115], v[180:183], v[188:191], v[112:115]
	v_mfma_f32_16x16x32_bf16 v[100:103], v[172:175], v[196:199], v[100:103]
	v_mfma_f32_16x16x32_bf16 v[96:99], v[180:183], v[196:199], v[96:99]
	s_setprio 2
	s_barrier
	v_mfma_f32_16x16x32_bf16 v[84:87], v[172:175], v[204:207], v[84:87]
	v_mfma_f32_16x16x32_bf16 v[80:83], v[180:183], v[204:207], v[80:83]
	v_mfma_f32_16x16x32_bf16 v[68:71], v[172:175], v[212:215], v[68:71]
	v_mfma_f32_16x16x32_bf16 v[64:67], v[180:183], v[212:215], v[64:67]
	s_setprio 0
	s_add_i32 s66, s59, s47
	v_lshl_add_u64 v[160:161], s[38:39], 0, v[132:133]
	s_mov_b32 m0, s66
	ds_read_b128 v[184:187], v165 offset:16384
	ds_read_b128 v[188:191], v165 offset:17408
	ds_read_b128 v[192:195], v165 offset:18432
	ds_read_b128 v[196:199], v165 offset:19456
	ds_read_b128 v[200:203], v165 offset:20480
	ds_read_b128 v[204:207], v165 offset:21504
	ds_read_b128 v[208:211], v165 offset:22528
	ds_read_b128 v[212:215], v165 offset:23552
	global_load_lds_dwordx4 v[160:161], off
	s_add_i32 m0, s66, 0x2000
	s_add_u32 s66, s38, 0x40000
	v_lshl_add_u64 v[216:217], s[38:39], 0, v[128:129]
	s_addc_u32 s67, s39, 0
	s_add_i32 s68, s60, s47
	global_load_lds_dwordx4 v[216:217], off
	v_lshl_add_u64 v[218:219], s[66:67], 0, v[132:133]
	s_mov_b32 m0, s68
	v_lshl_add_u64 v[220:221], s[40:41], 0, v[130:131]
	global_load_lds_dwordx4 v[218:219], off
	v_lshl_add_u64 v[218:219], s[66:67], 0, v[128:129]
	s_add_i32 m0, s68, 0x2000
	s_nop 0
	global_load_lds_dwordx4 v[218:219], off
	v_lshl_add_u64 v[218:219], s[40:41], 0, v[134:135]
	s_mov_b32 m0, s50
	s_nop 0
	global_load_lds_dwordx4 v[218:219], off
	s_mov_b32 m0, s51
	s_nop 0
	global_load_lds_dwordx4 v[220:221], off
	s_waitcnt vmcnt(8)
	s_waitcnt lgkmcnt(0)
	s_barrier
	s_setprio 1
	s_waitcnt lgkmcnt(0)
	v_mfma_f32_16x16x32_bf16 v[60:63], v[144:147], v[184:187], 0
	v_mfma_f32_16x16x32_bf16 v[56:59], v[152:155], v[184:187], 0
	v_mfma_f32_16x16x32_bf16 v[44:47], v[144:147], v[192:195], 0
	v_mfma_f32_16x16x32_bf16 v[40:43], v[152:155], v[192:195], 0
	v_mfma_f32_16x16x32_bf16 v[28:31], v[144:147], v[200:203], 0
	v_mfma_f32_16x16x32_bf16 v[24:27], v[152:155], v[200:203], 0
	v_mfma_f32_16x16x32_bf16 v[12:15], v[144:147], v[208:211], 0
	v_mfma_f32_16x16x32_bf16 v[8:11], v[152:155], v[208:211], 0
	v_mfma_f32_16x16x32_bf16 v[60:63], v[148:151], v[188:191], v[60:63]
	v_mfma_f32_16x16x32_bf16 v[56:59], v[156:159], v[188:191], v[56:59]
	v_mfma_f32_16x16x32_bf16 v[44:47], v[148:151], v[196:199], v[44:47]
	v_mfma_f32_16x16x32_bf16 v[40:43], v[156:159], v[196:199], v[40:43]
	v_mfma_f32_16x16x32_bf16 v[28:31], v[148:151], v[204:207], v[28:31]
	v_mfma_f32_16x16x32_bf16 v[24:27], v[156:159], v[204:207], v[24:27]
	v_mfma_f32_16x16x32_bf16 v[12:15], v[148:151], v[212:215], v[12:15]
	v_mfma_f32_16x16x32_bf16 v[8:11], v[156:159], v[212:215], v[8:11]
	s_setprio 0
	s_setprio 1
	v_mfma_f32_16x16x32_bf16 v[52:55], v[168:171], v[184:187], 0
	v_mfma_f32_16x16x32_bf16 v[48:51], v[176:179], v[184:187], 0
	v_mfma_f32_16x16x32_bf16 v[36:39], v[168:171], v[192:195], 0
	v_mfma_f32_16x16x32_bf16 v[32:35], v[176:179], v[192:195], 0
	v_mfma_f32_16x16x32_bf16 v[20:23], v[168:171], v[200:203], 0
	v_mfma_f32_16x16x32_bf16 v[16:19], v[176:179], v[200:203], 0
	v_mfma_f32_16x16x32_bf16 v[4:7], v[168:171], v[208:211], 0
	v_mfma_f32_16x16x32_bf16 v[0:3], v[176:179], v[208:211], 0
	v_mfma_f32_16x16x32_bf16 v[52:55], v[172:175], v[188:191], v[52:55]
	v_mfma_f32_16x16x32_bf16 v[48:51], v[180:183], v[188:191], v[48:51]
	v_mfma_f32_16x16x32_bf16 v[36:39], v[172:175], v[196:199], v[36:39]
	v_mfma_f32_16x16x32_bf16 v[32:35], v[180:183], v[196:199], v[32:35]
	s_setprio 2
	s_barrier
	v_mfma_f32_16x16x32_bf16 v[20:23], v[172:175], v[204:207], v[20:23]
	v_mfma_f32_16x16x32_bf16 v[16:19], v[180:183], v[204:207], v[16:19]
	v_mfma_f32_16x16x32_bf16 v[4:7], v[172:175], v[212:215], v[4:7]
	v_mfma_f32_16x16x32_bf16 v[0:3], v[180:183], v[212:215], v[0:3]
	s_setprio 0
	s_add_i32 s66, 0, 0x18000
	s_add_i32 s67, 0, 0x1c000
	v_add_u32_e32 v156, s66, v162
	v_add_u32_e32 v167, s67, v162
	ds_read_b128 v[144:147], v156
	ds_read_b128 v[148:151], v156 offset:1024
	ds_read_b128 v[152:155], v156 offset:2048
	ds_read_b128 v[156:159], v156 offset:3072
	ds_read_b128 v[168:171], v167
	ds_read_b128 v[172:175], v167 offset:1024
	ds_read_b128 v[176:179], v167 offset:2048
	ds_read_b128 v[180:183], v167 offset:3072
	s_add_u32 s40, s40, 0x40000
	s_addc_u32 s41, s41, 0
	s_mov_b32 m0, s54
	v_lshl_add_u64 v[222:223], s[40:41], 0, v[134:135]
	ds_read_b128 v[184:187], v165 offset:32768
	ds_read_b128 v[188:191], v165 offset:33792
	ds_read_b128 v[192:195], v165 offset:34816
	ds_read_b128 v[196:199], v165 offset:35840
	ds_read_b128 v[200:203], v165 offset:36864
	ds_read_b128 v[204:207], v165 offset:37888
	ds_read_b128 v[208:211], v165 offset:38912
	ds_read_b128 v[212:215], v165 offset:39936
	global_load_lds_dwordx4 v[222:223], off
	v_lshl_add_u64 v[222:223], s[40:41], 0, v[130:131]
	s_mov_b32 m0, s55
	s_nop 0
	global_load_lds_dwordx4 v[222:223], off
	s_waitcnt vmcnt(8)
	s_waitcnt lgkmcnt(0)
	s_barrier
	s_setprio 1
	s_waitcnt lgkmcnt(0)
	v_mfma_f32_16x16x32_bf16 v[124:127], v[144:147], v[184:187], v[124:127]
	v_mfma_f32_16x16x32_bf16 v[120:123], v[152:155], v[184:187], v[120:123]
	v_mfma_f32_16x16x32_bf16 v[108:111], v[144:147], v[192:195], v[108:111]
	v_mfma_f32_16x16x32_bf16 v[104:107], v[152:155], v[192:195], v[104:107]
	v_mfma_f32_16x16x32_bf16 v[92:95], v[144:147], v[200:203], v[92:95]
	v_mfma_f32_16x16x32_bf16 v[88:91], v[152:155], v[200:203], v[88:91]
	v_mfma_f32_16x16x32_bf16 v[76:79], v[144:147], v[208:211], v[76:79]
	v_mfma_f32_16x16x32_bf16 v[72:75], v[152:155], v[208:211], v[72:75]
	v_mfma_f32_16x16x32_bf16 v[124:127], v[148:151], v[188:191], v[124:127]
	v_mfma_f32_16x16x32_bf16 v[120:123], v[156:159], v[188:191], v[120:123]
	v_mfma_f32_16x16x32_bf16 v[108:111], v[148:151], v[196:199], v[108:111]
	v_mfma_f32_16x16x32_bf16 v[104:107], v[156:159], v[196:199], v[104:107]
	v_mfma_f32_16x16x32_bf16 v[92:95], v[148:151], v[204:207], v[92:95]
	v_mfma_f32_16x16x32_bf16 v[88:91], v[156:159], v[204:207], v[88:91]
	v_mfma_f32_16x16x32_bf16 v[76:79], v[148:151], v[212:215], v[76:79]
	v_mfma_f32_16x16x32_bf16 v[72:75], v[156:159], v[212:215], v[72:75]
	s_setprio 0
	s_setprio 1
	v_mfma_f32_16x16x32_bf16 v[116:119], v[168:171], v[184:187], v[116:119]
	v_mfma_f32_16x16x32_bf16 v[112:115], v[176:179], v[184:187], v[112:115]
	v_mfma_f32_16x16x32_bf16 v[100:103], v[168:171], v[192:195], v[100:103]
	v_mfma_f32_16x16x32_bf16 v[96:99], v[176:179], v[192:195], v[96:99]
	v_mfma_f32_16x16x32_bf16 v[84:87], v[168:171], v[200:203], v[84:87]
	v_mfma_f32_16x16x32_bf16 v[80:83], v[176:179], v[200:203], v[80:83]
	v_mfma_f32_16x16x32_bf16 v[68:71], v[168:171], v[208:211], v[68:71]
	v_mfma_f32_16x16x32_bf16 v[64:67], v[176:179], v[208:211], v[64:67]
	v_mfma_f32_16x16x32_bf16 v[116:119], v[172:175], v[188:191], v[116:119]
	v_mfma_f32_16x16x32_bf16 v[112:115], v[180:183], v[188:191], v[112:115]
	v_mfma_f32_16x16x32_bf16 v[100:103], v[172:175], v[196:199], v[100:103]
	v_mfma_f32_16x16x32_bf16 v[96:99], v[180:183], v[196:199], v[96:99]
	s_setprio 2
	s_barrier
	v_mfma_f32_16x16x32_bf16 v[84:87], v[172:175], v[204:207], v[84:87]
	v_mfma_f32_16x16x32_bf16 v[80:83], v[180:183], v[204:207], v[80:83]
	v_mfma_f32_16x16x32_bf16 v[68:71], v[172:175], v[212:215], v[68:71]
	v_mfma_f32_16x16x32_bf16 v[64:67], v[180:183], v[212:215], v[64:67]
	s_setprio 0
	s_add_i32 s40, s66, s47
	v_lshl_add_u64 v[160:161], v[160:161], 0, s[16:17]
	s_mov_b32 m0, s40
	ds_read_b128 v[184:187], v165 offset:49152
	ds_read_b128 v[188:191], v165 offset:50176
	ds_read_b128 v[192:195], v165 offset:51200
	ds_read_b128 v[196:199], v165 offset:52224
	ds_read_b128 v[200:203], v165 offset:53248
	ds_read_b128 v[204:207], v165 offset:54272
	ds_read_b128 v[208:211], v165 offset:55296
	ds_read_b128 v[212:215], v165 offset:56320
	global_load_lds_dwordx4 v[160:161], off
	s_add_i32 m0, s40, 0x2000
	s_add_u32 s38, s38, 0x40080
	v_lshl_add_u64 v[160:161], v[216:217], 0, s[16:17]
	s_addc_u32 s39, s39, 0
	s_add_i32 s40, s67, s47
	global_load_lds_dwordx4 v[160:161], off
	v_lshl_add_u64 v[160:161], s[38:39], 0, v[132:133]
	s_mov_b32 m0, s40
	s_nop 0
	global_load_lds_dwordx4 v[160:161], off
	v_lshl_add_u64 v[160:161], s[38:39], 0, v[128:129]
	s_add_i32 m0, s40, 0x2000
	s_nop 0
	global_load_lds_dwordx4 v[160:161], off
	v_lshl_add_u64 v[160:161], v[218:219], 0, s[16:17]
	s_mov_b32 m0, s57
	s_nop 0
	global_load_lds_dwordx4 v[160:161], off
	v_lshl_add_u64 v[160:161], v[220:221], 0, s[16:17]
	s_mov_b32 m0, s58
	s_nop 0
	global_load_lds_dwordx4 v[160:161], off
	s_waitcnt vmcnt(8)
	s_waitcnt lgkmcnt(0)
	s_barrier
	s_setprio 1
	s_waitcnt lgkmcnt(0)
	v_mfma_f32_16x16x32_bf16 v[60:63], v[144:147], v[184:187], v[60:63]
	v_mfma_f32_16x16x32_bf16 v[56:59], v[152:155], v[184:187], v[56:59]
	v_mfma_f32_16x16x32_bf16 v[44:47], v[144:147], v[192:195], v[44:47]
	v_mfma_f32_16x16x32_bf16 v[40:43], v[152:155], v[192:195], v[40:43]
	v_mfma_f32_16x16x32_bf16 v[28:31], v[144:147], v[200:203], v[28:31]
	v_mfma_f32_16x16x32_bf16 v[24:27], v[152:155], v[200:203], v[24:27]
	v_mfma_f32_16x16x32_bf16 v[12:15], v[144:147], v[208:211], v[12:15]
	v_mfma_f32_16x16x32_bf16 v[8:11], v[152:155], v[208:211], v[8:11]
	v_mfma_f32_16x16x32_bf16 v[60:63], v[148:151], v[188:191], v[60:63]
	v_mfma_f32_16x16x32_bf16 v[56:59], v[156:159], v[188:191], v[56:59]
	v_mfma_f32_16x16x32_bf16 v[44:47], v[148:151], v[196:199], v[44:47]
	v_mfma_f32_16x16x32_bf16 v[40:43], v[156:159], v[196:199], v[40:43]
	v_mfma_f32_16x16x32_bf16 v[28:31], v[148:151], v[204:207], v[28:31]
	v_mfma_f32_16x16x32_bf16 v[24:27], v[156:159], v[204:207], v[24:27]
	v_mfma_f32_16x16x32_bf16 v[12:15], v[148:151], v[212:215], v[12:15]
	v_mfma_f32_16x16x32_bf16 v[8:11], v[156:159], v[212:215], v[8:11]
	s_setprio 0
	s_setprio 1
	v_mfma_f32_16x16x32_bf16 v[52:55], v[168:171], v[184:187], v[52:55]
	v_mfma_f32_16x16x32_bf16 v[48:51], v[176:179], v[184:187], v[48:51]
	v_mfma_f32_16x16x32_bf16 v[36:39], v[168:171], v[192:195], v[36:39]
	v_mfma_f32_16x16x32_bf16 v[32:35], v[176:179], v[192:195], v[32:35]
	v_mfma_f32_16x16x32_bf16 v[20:23], v[168:171], v[200:203], v[20:23]
	v_mfma_f32_16x16x32_bf16 v[16:19], v[176:179], v[200:203], v[16:19]
	v_mfma_f32_16x16x32_bf16 v[4:7], v[168:171], v[208:211], v[4:7]
	v_mfma_f32_16x16x32_bf16 v[0:3], v[176:179], v[208:211], v[0:3]
	v_mfma_f32_16x16x32_bf16 v[52:55], v[172:175], v[188:191], v[52:55]
	v_mfma_f32_16x16x32_bf16 v[48:51], v[180:183], v[188:191], v[48:51]
	v_mfma_f32_16x16x32_bf16 v[36:39], v[172:175], v[196:199], v[36:39]
	v_mfma_f32_16x16x32_bf16 v[32:35], v[180:183], v[196:199], v[32:35]
	s_setprio 2
	s_barrier
	v_mfma_f32_16x16x32_bf16 v[20:23], v[172:175], v[204:207], v[20:23]
	v_mfma_f32_16x16x32_bf16 v[16:19], v[180:183], v[204:207], v[16:19]
	v_mfma_f32_16x16x32_bf16 v[4:7], v[172:175], v[212:215], v[4:7]
	v_mfma_f32_16x16x32_bf16 v[0:3], v[180:183], v[212:215], v[0:3]
	s_setprio 0
	s_add_i32 s65, s65, 2
	s_add_u32 s36, s36, 0x100
	s_addc_u32 s37, s37, 0
	s_add_u32 s63, s63, 0x100
	s_addc_u32 s64, s64, 0
	s_cmp_gt_u32 s65, 13

.LBB0_865:
	s_add_u32 s62, s28, 0x100
	s_addc_u32 s63, s29, 0
	s_mov_b32 s64, -2
	ds_read_b128 v[120:123], v233
	ds_read_b128 v[124:127], v233 offset:1024
	ds_read_b128 v[136:139], v233 offset:2048
	ds_read_b128 v[140:143], v233 offset:3072
	ds_read_b128 v[144:147], v234
	ds_read_b128 v[148:151], v234 offset:1024
	ds_read_b128 v[152:155], v234 offset:2048
	ds_read_b128 v[156:159], v234 offset:3072
	s_add_u32 s28, s26, 0x100
	s_addc_u32 s29, s27, 0
	s_cmp_eq_u32 s64, 40
	s_cselect_b32 s37, s7, s29
	s_cselect_b32 s36, s6, s28
	s_cselect_b32 s31, s25, s63
	s_cselect_b32 s30, s24, s62
	v_lshl_add_u64 v[208:209], s[26:27], 0, v[192:193]
	s_add_i32 m0, s44, 0xc000
	ds_read_b128 v[160:163], v235
	ds_read_b128 v[164:167], v235 offset:1024
	ds_read_b128 v[168:171], v235 offset:2048
	ds_read_b128 v[172:175], v235 offset:3072
	ds_read_b128 v[176:179], v235 offset:4096
	ds_read_b128 v[180:183], v235 offset:5120
	ds_read_b128 v[200:203], v235 offset:6144
	ds_read_b128 v[204:207], v235 offset:7168
	global_load_lds_dwordx4 v[208:209], off
	v_lshl_add_u64 v[208:209], s[26:27], 0, v[194:195]
	s_add_i32 m0, s44, 0xe000
	s_nop 0
	global_load_lds_dwordx4 v[208:209], off
	s_waitcnt vmcnt(8)
	s_waitcnt lgkmcnt(0)
	s_barrier
	s_setprio 1
	s_waitcnt lgkmcnt(0)
	v_mfma_f32_16x16x32_bf16 v[132:135], v[120:123], v[160:163], 0
	v_mfma_f32_16x16x32_bf16 v[128:131], v[136:139], v[160:163], 0
	v_mfma_f32_16x16x32_bf16 v[108:111], v[120:123], v[168:171], 0
	v_mfma_f32_16x16x32_bf16 v[104:107], v[136:139], v[168:171], 0
	v_mfma_f32_16x16x32_bf16 v[92:95], v[120:123], v[176:179], 0
	v_mfma_f32_16x16x32_bf16 v[88:91], v[136:139], v[176:179], 0
	v_mfma_f32_16x16x32_bf16 v[76:79], v[120:123], v[200:203], 0
	v_mfma_f32_16x16x32_bf16 v[72:75], v[136:139], v[200:203], 0
	v_mfma_f32_16x16x32_bf16 v[132:135], v[124:127], v[164:167], v[132:135]
	v_mfma_f32_16x16x32_bf16 v[128:131], v[140:143], v[164:167], v[128:131]
	v_mfma_f32_16x16x32_bf16 v[108:111], v[124:127], v[172:175], v[108:111]
	v_mfma_f32_16x16x32_bf16 v[104:107], v[140:143], v[172:175], v[104:107]
	v_mfma_f32_16x16x32_bf16 v[92:95], v[124:127], v[180:183], v[92:95]
	v_mfma_f32_16x16x32_bf16 v[88:91], v[140:143], v[180:183], v[88:91]
	v_mfma_f32_16x16x32_bf16 v[76:79], v[124:127], v[204:207], v[76:79]
	v_mfma_f32_16x16x32_bf16 v[72:75], v[140:143], v[204:207], v[72:75]
	s_setprio 0
	s_setprio 1
	v_mfma_f32_16x16x32_bf16 v[116:119], v[144:147], v[160:163], 0
	v_mfma_f32_16x16x32_bf16 v[112:115], v[152:155], v[160:163], 0
	v_mfma_f32_16x16x32_bf16 v[100:103], v[144:147], v[168:171], 0
	v_mfma_f32_16x16x32_bf16 v[96:99], v[152:155], v[168:171], 0
	v_mfma_f32_16x16x32_bf16 v[84:87], v[144:147], v[176:179], 0
	v_mfma_f32_16x16x32_bf16 v[80:83], v[152:155], v[176:179], 0
	v_mfma_f32_16x16x32_bf16 v[68:71], v[144:147], v[200:203], 0
	v_mfma_f32_16x16x32_bf16 v[64:67], v[152:155], v[200:203], 0
	v_mfma_f32_16x16x32_bf16 v[116:119], v[148:151], v[164:167], v[116:119]
	v_mfma_f32_16x16x32_bf16 v[112:115], v[156:159], v[164:167], v[112:115]
	v_mfma_f32_16x16x32_bf16 v[100:103], v[148:151], v[172:175], v[100:103]
	v_mfma_f32_16x16x32_bf16 v[96:99], v[156:159], v[172:175], v[96:99]
	s_setprio 2
	s_barrier
	v_mfma_f32_16x16x32_bf16 v[84:87], v[148:151], v[180:183], v[84:87]
	v_mfma_f32_16x16x32_bf16 v[80:83], v[156:159], v[180:183], v[80:83]
	v_mfma_f32_16x16x32_bf16 v[68:71], v[148:151], v[204:207], v[68:71]
	v_mfma_f32_16x16x32_bf16 v[64:67], v[156:159], v[204:207], v[64:67]
	s_setprio 0
	s_add_i32 s26, s56, s43
	v_lshl_add_u64 v[208:209], s[30:31], 0, v[186:187]
	s_mov_b32 m0, s26
	ds_read_b128 v[160:163], v235 offset:16384
	ds_read_b128 v[164:167], v235 offset:17408
	ds_read_b128 v[168:171], v235 offset:18432
	ds_read_b128 v[172:175], v235 offset:19456
	ds_read_b128 v[176:179], v235 offset:20480
	ds_read_b128 v[180:183], v235 offset:21504
	ds_read_b128 v[200:203], v235 offset:22528
	ds_read_b128 v[204:207], v235 offset:23552
	global_load_lds_dwordx4 v[208:209], off
	s_add_i32 m0, s26, 0x2000
	s_add_u32 s26, s30, 0xb0000
	v_lshl_add_u64 v[210:211], s[30:31], 0, v[190:191]
	s_addc_u32 s27, s31, 0
	s_add_i32 s65, s57, s43
	global_load_lds_dwordx4 v[210:211], off
	v_lshl_add_u64 v[212:213], s[26:27], 0, v[186:187]
	s_mov_b32 m0, s65
	v_lshl_add_u64 v[214:215], s[36:37], 0, v[188:189]
	global_load_lds_dwordx4 v[212:213], off
	v_lshl_add_u64 v[212:213], s[26:27], 0, v[190:191]
	s_add_i32 m0, s65, 0x2000
	s_nop 0
	global_load_lds_dwordx4 v[212:213], off
	v_lshl_add_u64 v[212:213], s[36:37], 0, v[184:185]
	s_mov_b32 m0, s44
	s_nop 0
	global_load_lds_dwordx4 v[212:213], off
	s_mov_b32 m0, s45
	s_nop 0
	global_load_lds_dwordx4 v[214:215], off
	s_waitcnt vmcnt(8)
	s_waitcnt lgkmcnt(0)
	s_barrier
	s_setprio 1
	s_waitcnt lgkmcnt(0)
	v_mfma_f32_16x16x32_bf16 v[60:63], v[120:123], v[160:163], 0
	v_mfma_f32_16x16x32_bf16 v[56:59], v[136:139], v[160:163], 0
	v_mfma_f32_16x16x32_bf16 v[44:47], v[120:123], v[168:171], 0
	v_mfma_f32_16x16x32_bf16 v[40:43], v[136:139], v[168:171], 0
	v_mfma_f32_16x16x32_bf16 v[28:31], v[120:123], v[176:179], 0
	v_mfma_f32_16x16x32_bf16 v[24:27], v[136:139], v[176:179], 0
	v_mfma_f32_16x16x32_bf16 v[12:15], v[120:123], v[200:203], 0
	v_mfma_f32_16x16x32_bf16 v[8:11], v[136:139], v[200:203], 0
	v_mfma_f32_16x16x32_bf16 v[60:63], v[124:127], v[164:167], v[60:63]
	v_mfma_f32_16x16x32_bf16 v[56:59], v[140:143], v[164:167], v[56:59]
	v_mfma_f32_16x16x32_bf16 v[44:47], v[124:127], v[172:175], v[44:47]
	v_mfma_f32_16x16x32_bf16 v[40:43], v[140:143], v[172:175], v[40:43]
	v_mfma_f32_16x16x32_bf16 v[28:31], v[124:127], v[180:183], v[28:31]
	v_mfma_f32_16x16x32_bf16 v[24:27], v[140:143], v[180:183], v[24:27]
	v_mfma_f32_16x16x32_bf16 v[12:15], v[124:127], v[204:207], v[12:15]
	v_mfma_f32_16x16x32_bf16 v[8:11], v[140:143], v[204:207], v[8:11]
	s_setprio 0
	s_setprio 1
	v_mfma_f32_16x16x32_bf16 v[52:55], v[144:147], v[160:163], 0
	v_mfma_f32_16x16x32_bf16 v[48:51], v[152:155], v[160:163], 0
	v_mfma_f32_16x16x32_bf16 v[36:39], v[144:147], v[168:171], 0
	v_mfma_f32_16x16x32_bf16 v[32:35], v[152:155], v[168:171], 0
	v_mfma_f32_16x16x32_bf16 v[20:23], v[144:147], v[176:179], 0
	v_mfma_f32_16x16x32_bf16 v[16:19], v[152:155], v[176:179], 0
	v_mfma_f32_16x16x32_bf16 v[4:7], v[144:147], v[200:203], 0
	v_mfma_f32_16x16x32_bf16 v[0:3], v[152:155], v[200:203], 0
	v_mfma_f32_16x16x32_bf16 v[52:55], v[148:151], v[164:167], v[52:55]
	v_mfma_f32_16x16x32_bf16 v[48:51], v[156:159], v[164:167], v[48:51]
	v_mfma_f32_16x16x32_bf16 v[36:39], v[148:151], v[172:175], v[36:39]
	v_mfma_f32_16x16x32_bf16 v[32:35], v[156:159], v[172:175], v[32:35]
	s_setprio 2
	s_barrier
	v_mfma_f32_16x16x32_bf16 v[20:23], v[148:151], v[180:183], v[20:23]
	v_mfma_f32_16x16x32_bf16 v[16:19], v[156:159], v[180:183], v[16:19]
	v_mfma_f32_16x16x32_bf16 v[4:7], v[148:151], v[204:207], v[4:7]
	v_mfma_f32_16x16x32_bf16 v[0:3], v[156:159], v[204:207], v[0:3]
	s_setprio 0
	s_add_i32 s65, 0, 0x18000
	s_add_i32 s66, 0, 0x1c000
	v_add_u32_e32 v140, s65, v232
	v_add_u32_e32 v156, s66, v232
	ds_read_b128 v[120:123], v140
	ds_read_b128 v[124:127], v140 offset:1024
	ds_read_b128 v[136:139], v140 offset:2048
	ds_read_b128 v[140:143], v140 offset:3072
	ds_read_b128 v[144:147], v156
	ds_read_b128 v[148:151], v156 offset:1024
	ds_read_b128 v[152:155], v156 offset:2048
	ds_read_b128 v[156:159], v156 offset:3072
	s_add_u32 s26, s36, 0xb0000
	s_addc_u32 s27, s37, 0
	s_mov_b32 m0, s46
	v_lshl_add_u64 v[216:217], s[26:27], 0, v[184:185]
	ds_read_b128 v[160:163], v235 offset:32768
	ds_read_b128 v[164:167], v235 offset:33792
	ds_read_b128 v[168:171], v235 offset:34816
	ds_read_b128 v[172:175], v235 offset:35840
	ds_read_b128 v[176:179], v235 offset:36864
	ds_read_b128 v[180:183], v235 offset:37888
	ds_read_b128 v[200:203], v235 offset:38912
	ds_read_b128 v[204:207], v235 offset:39936
	global_load_lds_dwordx4 v[216:217], off
	v_lshl_add_u64 v[216:217], s[26:27], 0, v[188:189]
	s_mov_b32 m0, s47
	s_nop 0
	global_load_lds_dwordx4 v[216:217], off
	s_waitcnt vmcnt(8)
	s_waitcnt lgkmcnt(0)
	s_barrier
	s_setprio 1
	s_waitcnt lgkmcnt(0)
	v_mfma_f32_16x16x32_bf16 v[132:135], v[120:123], v[160:163], v[132:135]
	v_mfma_f32_16x16x32_bf16 v[128:131], v[136:139], v[160:163], v[128:131]
	v_mfma_f32_16x16x32_bf16 v[108:111], v[120:123], v[168:171], v[108:111]
	v_mfma_f32_16x16x32_bf16 v[104:107], v[136:139], v[168:171], v[104:107]
	v_mfma_f32_16x16x32_bf16 v[92:95], v[120:123], v[176:179], v[92:95]
	v_mfma_f32_16x16x32_bf16 v[88:91], v[136:139], v[176:179], v[88:91]
	v_mfma_f32_16x16x32_bf16 v[76:79], v[120:123], v[200:203], v[76:79]
	v_mfma_f32_16x16x32_bf16 v[72:75], v[136:139], v[200:203], v[72:75]
	v_mfma_f32_16x16x32_bf16 v[132:135], v[124:127], v[164:167], v[132:135]
	v_mfma_f32_16x16x32_bf16 v[128:131], v[140:143], v[164:167], v[128:131]
	v_mfma_f32_16x16x32_bf16 v[108:111], v[124:127], v[172:175], v[108:111]
	v_mfma_f32_16x16x32_bf16 v[104:107], v[140:143], v[172:175], v[104:107]
	v_mfma_f32_16x16x32_bf16 v[92:95], v[124:127], v[180:183], v[92:95]
	v_mfma_f32_16x16x32_bf16 v[88:91], v[140:143], v[180:183], v[88:91]
	v_mfma_f32_16x16x32_bf16 v[76:79], v[124:127], v[204:207], v[76:79]
	v_mfma_f32_16x16x32_bf16 v[72:75], v[140:143], v[204:207], v[72:75]
	s_setprio 0
	s_setprio 1
	v_mfma_f32_16x16x32_bf16 v[116:119], v[144:147], v[160:163], v[116:119]
	v_mfma_f32_16x16x32_bf16 v[112:115], v[152:155], v[160:163], v[112:115]
	v_mfma_f32_16x16x32_bf16 v[100:103], v[144:147], v[168:171], v[100:103]
	v_mfma_f32_16x16x32_bf16 v[96:99], v[152:155], v[168:171], v[96:99]
	v_mfma_f32_16x16x32_bf16 v[84:87], v[144:147], v[176:179], v[84:87]
	v_mfma_f32_16x16x32_bf16 v[80:83], v[152:155], v[176:179], v[80:83]
	v_mfma_f32_16x16x32_bf16 v[68:71], v[144:147], v[200:203], v[68:71]
	v_mfma_f32_16x16x32_bf16 v[64:67], v[152:155], v[200:203], v[64:67]
	v_mfma_f32_16x16x32_bf16 v[116:119], v[148:151], v[164:167], v[116:119]
	v_mfma_f32_16x16x32_bf16 v[112:115], v[156:159], v[164:167], v[112:115]
	v_mfma_f32_16x16x32_bf16 v[100:103], v[148:151], v[172:175], v[100:103]
	v_mfma_f32_16x16x32_bf16 v[96:99], v[156:159], v[172:175], v[96:99]
	s_setprio 2
	s_barrier
	v_mfma_f32_16x16x32_bf16 v[84:87], v[148:151], v[180:183], v[84:87]
	v_mfma_f32_16x16x32_bf16 v[80:83], v[156:159], v[180:183], v[80:83]
	v_mfma_f32_16x16x32_bf16 v[68:71], v[148:151], v[204:207], v[68:71]
	v_mfma_f32_16x16x32_bf16 v[64:67], v[156:159], v[204:207], v[64:67]
	s_setprio 0
	s_add_i32 s26, s65, s43
	v_lshl_add_u64 v[208:209], v[208:209], 0, s[20:21]
	s_mov_b32 m0, s26
	ds_read_b128 v[160:163], v235 offset:49152
	ds_read_b128 v[164:167], v235 offset:50176
	ds_read_b128 v[168:171], v235 offset:51200
	ds_read_b128 v[172:175], v235 offset:52224
	ds_read_b128 v[176:179], v235 offset:53248
	ds_read_b128 v[180:183], v235 offset:54272
	ds_read_b128 v[200:203], v235 offset:55296
	ds_read_b128 v[204:207], v235 offset:56320
	global_load_lds_dwordx4 v[208:209], off
	s_add_i32 m0, s26, 0x2000
	s_add_u32 s26, s30, 0xb0080
	v_lshl_add_u64 v[208:209], v[210:211], 0, s[20:21]
	s_addc_u32 s27, s31, 0
	s_add_i32 s30, s66, s43
	global_load_lds_dwordx4 v[208:209], off
	v_lshl_add_u64 v[208:209], s[26:27], 0, v[186:187]
	s_mov_b32 m0, s30
	s_nop 0
	global_load_lds_dwordx4 v[208:209], off
	v_lshl_add_u64 v[208:209], s[26:27], 0, v[190:191]
	s_add_i32 m0, s30, 0x2000
	s_nop 0
	global_load_lds_dwordx4 v[208:209], off
	v_lshl_add_u64 v[208:209], v[212:213], 0, s[20:21]
	s_mov_b32 m0, s49
	s_nop 0
	global_load_lds_dwordx4 v[208:209], off
	v_lshl_add_u64 v[208:209], v[214:215], 0, s[20:21]
	s_mov_b32 m0, s50
	s_nop 0
	global_load_lds_dwordx4 v[208:209], off
	s_waitcnt vmcnt(8)
	s_waitcnt lgkmcnt(0)
	s_barrier
	s_setprio 1
	s_waitcnt lgkmcnt(0)
	v_mfma_f32_16x16x32_bf16 v[60:63], v[120:123], v[160:163], v[60:63]
	v_mfma_f32_16x16x32_bf16 v[56:59], v[136:139], v[160:163], v[56:59]
	v_mfma_f32_16x16x32_bf16 v[44:47], v[120:123], v[168:171], v[44:47]
	v_mfma_f32_16x16x32_bf16 v[40:43], v[136:139], v[168:171], v[40:43]
	v_mfma_f32_16x16x32_bf16 v[28:31], v[120:123], v[176:179], v[28:31]
	v_mfma_f32_16x16x32_bf16 v[24:27], v[136:139], v[176:179], v[24:27]
	v_mfma_f32_16x16x32_bf16 v[12:15], v[120:123], v[200:203], v[12:15]
	v_mfma_f32_16x16x32_bf16 v[8:11], v[136:139], v[200:203], v[8:11]
	v_mfma_f32_16x16x32_bf16 v[60:63], v[124:127], v[164:167], v[60:63]
	v_mfma_f32_16x16x32_bf16 v[56:59], v[140:143], v[164:167], v[56:59]
	v_mfma_f32_16x16x32_bf16 v[44:47], v[124:127], v[172:175], v[44:47]
	v_mfma_f32_16x16x32_bf16 v[40:43], v[140:143], v[172:175], v[40:43]
	v_mfma_f32_16x16x32_bf16 v[28:31], v[124:127], v[180:183], v[28:31]
	v_mfma_f32_16x16x32_bf16 v[24:27], v[140:143], v[180:183], v[24:27]
	v_mfma_f32_16x16x32_bf16 v[12:15], v[124:127], v[204:207], v[12:15]
	v_mfma_f32_16x16x32_bf16 v[8:11], v[140:143], v[204:207], v[8:11]
	s_setprio 0
	s_setprio 1
	v_mfma_f32_16x16x32_bf16 v[52:55], v[144:147], v[160:163], v[52:55]
	v_mfma_f32_16x16x32_bf16 v[48:51], v[152:155], v[160:163], v[48:51]
	v_mfma_f32_16x16x32_bf16 v[36:39], v[144:147], v[168:171], v[36:39]
	v_mfma_f32_16x16x32_bf16 v[32:35], v[152:155], v[168:171], v[32:35]
	v_mfma_f32_16x16x32_bf16 v[20:23], v[144:147], v[176:179], v[20:23]
	v_mfma_f32_16x16x32_bf16 v[16:19], v[152:155], v[176:179], v[16:19]
	v_mfma_f32_16x16x32_bf16 v[4:7], v[144:147], v[200:203], v[4:7]
	v_mfma_f32_16x16x32_bf16 v[0:3], v[152:155], v[200:203], v[0:3]
	v_mfma_f32_16x16x32_bf16 v[52:55], v[148:151], v[164:167], v[52:55]
	v_mfma_f32_16x16x32_bf16 v[48:51], v[156:159], v[164:167], v[48:51]
	v_mfma_f32_16x16x32_bf16 v[36:39], v[148:151], v[172:175], v[36:39]
	v_mfma_f32_16x16x32_bf16 v[32:35], v[156:159], v[172:175], v[32:35]
	s_setprio 2
	s_barrier
	v_mfma_f32_16x16x32_bf16 v[20:23], v[148:151], v[180:183], v[20:23]
	v_mfma_f32_16x16x32_bf16 v[16:19], v[156:159], v[180:183], v[16:19]
	v_mfma_f32_16x16x32_bf16 v[4:7], v[148:151], v[204:207], v[4:7]
	v_mfma_f32_16x16x32_bf16 v[0:3], v[156:159], v[204:207], v[0:3]
	s_setprio 0
	s_add_i32 s64, s64, 2
	s_add_u32 s62, s62, 0x100
	s_addc_u32 s63, s63, 0
	s_cmp_gt_u32 s64, 41
	s_mov_b64 s[26:27], s[28:29]

.LBB0_951:
	s_ashr_i32 s27, s26, 31
	s_lshl_b64 s[30:31], s[26:27], 19
	s_add_u32 s30, s47, s30
	s_addc_u32 s31, s48, s31
	s_and_b64 s[36:37], s[4:5], exec
	s_cselect_b32 s27, s31, s7
	s_cselect_b32 s39, s30, s6
	s_ashr_i32 s29, s28, 31
	s_lshl_b64 s[36:37], s[28:29], 19
	s_add_u32 s36, s49, s36
	s_addc_u32 s37, s50, s37
	s_and_b64 s[44:45], s[4:5], exec
	s_cselect_b32 s29, s37, s41
	s_cselect_b32 s43, s36, s40
	s_add_u32 s6, s6, 0x40080
	s_addc_u32 s7, s7, 0
	s_add_u32 s71, s40, 0x100
	s_addc_u32 s72, s41, 0
	s_mov_b32 s73, -2
	ds_read_b128 v[144:147], v179
	ds_read_b128 v[148:151], v179 offset:1024
	ds_read_b128 v[152:155], v179 offset:2048
	ds_read_b128 v[156:159], v179 offset:3072
	ds_read_b128 v[160:163], v180
	ds_read_b128 v[164:167], v180 offset:1024
	ds_read_b128 v[168:171], v180 offset:2048
	ds_read_b128 v[172:175], v180 offset:3072
	s_add_u32 s40, s6, 0xfffc0080
	s_addc_u32 s41, s7, -1
	s_cmp_eq_u32 s73, 12
	s_cselect_b32 s45, s27, s41
	s_cselect_b32 s44, s39, s40
	s_cselect_b32 s41, s29, s72
	s_cselect_b32 s40, s43, s71
	v_lshl_add_u64 v[176:177], s[6:7], 0, v[136:137]
	s_add_i32 m0, s54, 0xc000
	ds_read_b128 v[184:187], v181
	ds_read_b128 v[188:191], v181 offset:1024
	ds_read_b128 v[192:195], v181 offset:2048
	ds_read_b128 v[196:199], v181 offset:3072
	ds_read_b128 v[200:203], v181 offset:4096
	ds_read_b128 v[204:207], v181 offset:5120
	ds_read_b128 v[208:211], v181 offset:6144
	ds_read_b128 v[212:215], v181 offset:7168
	global_load_lds_dwordx4 v[176:177], off
	v_lshl_add_u64 v[176:177], s[6:7], 0, v[138:139]
	s_add_i32 m0, s54, 0xe000
	s_nop 0
	global_load_lds_dwordx4 v[176:177], off
	s_waitcnt vmcnt(8)
	s_waitcnt lgkmcnt(0)
	s_barrier
	s_setprio 1
	s_waitcnt lgkmcnt(0)
	v_mfma_f32_16x16x32_bf16 v[124:127], v[144:147], v[184:187], 0
	v_mfma_f32_16x16x32_bf16 v[120:123], v[152:155], v[184:187], 0
	v_mfma_f32_16x16x32_bf16 v[108:111], v[144:147], v[192:195], 0
	v_mfma_f32_16x16x32_bf16 v[104:107], v[152:155], v[192:195], 0
	v_mfma_f32_16x16x32_bf16 v[92:95], v[144:147], v[200:203], 0
	v_mfma_f32_16x16x32_bf16 v[88:91], v[152:155], v[200:203], 0
	v_mfma_f32_16x16x32_bf16 v[76:79], v[144:147], v[208:211], 0
	v_mfma_f32_16x16x32_bf16 v[72:75], v[152:155], v[208:211], 0
	v_mfma_f32_16x16x32_bf16 v[124:127], v[148:151], v[188:191], v[124:127]
	v_mfma_f32_16x16x32_bf16 v[120:123], v[156:159], v[188:191], v[120:123]
	v_mfma_f32_16x16x32_bf16 v[108:111], v[148:151], v[196:199], v[108:111]
	v_mfma_f32_16x16x32_bf16 v[104:107], v[156:159], v[196:199], v[104:107]
	v_mfma_f32_16x16x32_bf16 v[92:95], v[148:151], v[204:207], v[92:95]
	v_mfma_f32_16x16x32_bf16 v[88:91], v[156:159], v[204:207], v[88:91]
	v_mfma_f32_16x16x32_bf16 v[76:79], v[148:151], v[212:215], v[76:79]
	v_mfma_f32_16x16x32_bf16 v[72:75], v[156:159], v[212:215], v[72:75]
	s_setprio 0
	s_setprio 1
	v_mfma_f32_16x16x32_bf16 v[116:119], v[160:163], v[184:187], 0
	v_mfma_f32_16x16x32_bf16 v[112:115], v[168:171], v[184:187], 0
	v_mfma_f32_16x16x32_bf16 v[100:103], v[160:163], v[192:195], 0
	v_mfma_f32_16x16x32_bf16 v[96:99], v[168:171], v[192:195], 0
	v_mfma_f32_16x16x32_bf16 v[84:87], v[160:163], v[200:203], 0
	v_mfma_f32_16x16x32_bf16 v[80:83], v[168:171], v[200:203], 0
	v_mfma_f32_16x16x32_bf16 v[68:71], v[160:163], v[208:211], 0
	v_mfma_f32_16x16x32_bf16 v[64:67], v[168:171], v[208:211], 0
	v_mfma_f32_16x16x32_bf16 v[116:119], v[164:167], v[188:191], v[116:119]
	v_mfma_f32_16x16x32_bf16 v[112:115], v[172:175], v[188:191], v[112:115]
	v_mfma_f32_16x16x32_bf16 v[100:103], v[164:167], v[196:199], v[100:103]
	v_mfma_f32_16x16x32_bf16 v[96:99], v[172:175], v[196:199], v[96:99]
	s_setprio 2
	s_barrier
	v_mfma_f32_16x16x32_bf16 v[84:87], v[164:167], v[204:207], v[84:87]
	v_mfma_f32_16x16x32_bf16 v[80:83], v[172:175], v[204:207], v[80:83]
	v_mfma_f32_16x16x32_bf16 v[68:71], v[164:167], v[212:215], v[68:71]
	v_mfma_f32_16x16x32_bf16 v[64:67], v[172:175], v[212:215], v[64:67]
	s_setprio 0
	s_add_i32 s74, s69, s51
	v_lshl_add_u64 v[176:177], s[40:41], 0, v[130:131]
	s_mov_b32 m0, s74
	ds_read_b128 v[184:187], v181 offset:16384
	ds_read_b128 v[188:191], v181 offset:17408
	ds_read_b128 v[192:195], v181 offset:18432
	ds_read_b128 v[196:199], v181 offset:19456
	ds_read_b128 v[200:203], v181 offset:20480
	ds_read_b128 v[204:207], v181 offset:21504
	ds_read_b128 v[208:211], v181 offset:22528
	ds_read_b128 v[212:215], v181 offset:23552
	global_load_lds_dwordx4 v[176:177], off
	s_add_i32 m0, s74, 0x2000
	s_add_u32 s74, s40, 0x40000
	v_lshl_add_u64 v[216:217], s[40:41], 0, v[134:135]
	s_addc_u32 s75, s41, 0
	s_add_i32 s76, s70, s51
	global_load_lds_dwordx4 v[216:217], off
	v_lshl_add_u64 v[218:219], s[74:75], 0, v[130:131]
	s_mov_b32 m0, s76
	v_lshl_add_u64 v[220:221], s[44:45], 0, v[132:133]
	global_load_lds_dwordx4 v[218:219], off
	v_lshl_add_u64 v[218:219], s[74:75], 0, v[134:135]
	s_add_i32 m0, s76, 0x2000
	s_nop 0
	global_load_lds_dwordx4 v[218:219], off
	v_lshl_add_u64 v[218:219], s[44:45], 0, v[128:129]
	s_mov_b32 m0, s54
	s_nop 0
	global_load_lds_dwordx4 v[218:219], off
	s_mov_b32 m0, s55
	s_nop 0
	global_load_lds_dwordx4 v[220:221], off
	s_waitcnt vmcnt(8)
	s_waitcnt lgkmcnt(0)
	s_barrier
	s_setprio 1
	s_waitcnt lgkmcnt(0)
	v_mfma_f32_16x16x32_bf16 v[60:63], v[144:147], v[184:187], 0
	v_mfma_f32_16x16x32_bf16 v[56:59], v[152:155], v[184:187], 0
	v_mfma_f32_16x16x32_bf16 v[44:47], v[144:147], v[192:195], 0
	v_mfma_f32_16x16x32_bf16 v[40:43], v[152:155], v[192:195], 0
	v_mfma_f32_16x16x32_bf16 v[28:31], v[144:147], v[200:203], 0
	v_mfma_f32_16x16x32_bf16 v[24:27], v[152:155], v[200:203], 0
	v_mfma_f32_16x16x32_bf16 v[12:15], v[144:147], v[208:211], 0
	v_mfma_f32_16x16x32_bf16 v[8:11], v[152:155], v[208:211], 0
	v_mfma_f32_16x16x32_bf16 v[60:63], v[148:151], v[188:191], v[60:63]
	v_mfma_f32_16x16x32_bf16 v[56:59], v[156:159], v[188:191], v[56:59]
	v_mfma_f32_16x16x32_bf16 v[44:47], v[148:151], v[196:199], v[44:47]
	v_mfma_f32_16x16x32_bf16 v[40:43], v[156:159], v[196:199], v[40:43]
	v_mfma_f32_16x16x32_bf16 v[28:31], v[148:151], v[204:207], v[28:31]
	v_mfma_f32_16x16x32_bf16 v[24:27], v[156:159], v[204:207], v[24:27]
	v_mfma_f32_16x16x32_bf16 v[12:15], v[148:151], v[212:215], v[12:15]
	v_mfma_f32_16x16x32_bf16 v[8:11], v[156:159], v[212:215], v[8:11]
	s_setprio 0
	s_setprio 1
	v_mfma_f32_16x16x32_bf16 v[52:55], v[160:163], v[184:187], 0
	v_mfma_f32_16x16x32_bf16 v[48:51], v[168:171], v[184:187], 0
	v_mfma_f32_16x16x32_bf16 v[36:39], v[160:163], v[192:195], 0
	v_mfma_f32_16x16x32_bf16 v[32:35], v[168:171], v[192:195], 0
	v_mfma_f32_16x16x32_bf16 v[20:23], v[160:163], v[200:203], 0
	v_mfma_f32_16x16x32_bf16 v[16:19], v[168:171], v[200:203], 0
	v_mfma_f32_16x16x32_bf16 v[4:7], v[160:163], v[208:211], 0
	v_mfma_f32_16x16x32_bf16 v[0:3], v[168:171], v[208:211], 0
	v_mfma_f32_16x16x32_bf16 v[52:55], v[164:167], v[188:191], v[52:55]
	v_mfma_f32_16x16x32_bf16 v[48:51], v[172:175], v[188:191], v[48:51]
	v_mfma_f32_16x16x32_bf16 v[36:39], v[164:167], v[196:199], v[36:39]
	v_mfma_f32_16x16x32_bf16 v[32:35], v[172:175], v[196:199], v[32:35]
	s_setprio 2
	s_barrier
	v_mfma_f32_16x16x32_bf16 v[20:23], v[164:167], v[204:207], v[20:23]
	v_mfma_f32_16x16x32_bf16 v[16:19], v[172:175], v[204:207], v[16:19]
	v_mfma_f32_16x16x32_bf16 v[4:7], v[164:167], v[212:215], v[4:7]
	v_mfma_f32_16x16x32_bf16 v[0:3], v[172:175], v[212:215], v[0:3]
	s_setprio 0
	s_add_i32 s74, 0, 0x18000
	s_add_i32 s75, 0, 0x1c000
	v_add_u32_e32 v156, s74, v178
	v_add_u32_e32 v172, s75, v178
	ds_read_b128 v[144:147], v156
	ds_read_b128 v[148:151], v156 offset:1024
	ds_read_b128 v[152:155], v156 offset:2048
	ds_read_b128 v[156:159], v156 offset:3072
	ds_read_b128 v[160:163], v172
	ds_read_b128 v[164:167], v172 offset:1024
	ds_read_b128 v[168:171], v172 offset:2048
	ds_read_b128 v[172:175], v172 offset:3072
	s_add_u32 s44, s44, 0x40000
	s_addc_u32 s45, s45, 0
	s_mov_b32 m0, s56
	v_lshl_add_u64 v[222:223], s[44:45], 0, v[128:129]
	ds_read_b128 v[184:187], v181 offset:32768
	ds_read_b128 v[188:191], v181 offset:33792
	ds_read_b128 v[192:195], v181 offset:34816
	ds_read_b128 v[196:199], v181 offset:35840
	ds_read_b128 v[200:203], v181 offset:36864
	ds_read_b128 v[204:207], v181 offset:37888
	ds_read_b128 v[208:211], v181 offset:38912
	ds_read_b128 v[212:215], v181 offset:39936
	global_load_lds_dwordx4 v[222:223], off
	v_lshl_add_u64 v[222:223], s[44:45], 0, v[132:133]
	s_mov_b32 m0, s57
	s_nop 0
	global_load_lds_dwordx4 v[222:223], off
	s_waitcnt vmcnt(8)
	s_waitcnt lgkmcnt(0)
	s_barrier
	s_setprio 1
	s_waitcnt lgkmcnt(0)
	v_mfma_f32_16x16x32_bf16 v[124:127], v[144:147], v[184:187], v[124:127]
	v_mfma_f32_16x16x32_bf16 v[120:123], v[152:155], v[184:187], v[120:123]
	v_mfma_f32_16x16x32_bf16 v[108:111], v[144:147], v[192:195], v[108:111]
	v_mfma_f32_16x16x32_bf16 v[104:107], v[152:155], v[192:195], v[104:107]
	v_mfma_f32_16x16x32_bf16 v[92:95], v[144:147], v[200:203], v[92:95]
	v_mfma_f32_16x16x32_bf16 v[88:91], v[152:155], v[200:203], v[88:91]
	v_mfma_f32_16x16x32_bf16 v[76:79], v[144:147], v[208:211], v[76:79]
	v_mfma_f32_16x16x32_bf16 v[72:75], v[152:155], v[208:211], v[72:75]
	v_mfma_f32_16x16x32_bf16 v[124:127], v[148:151], v[188:191], v[124:127]
	v_mfma_f32_16x16x32_bf16 v[120:123], v[156:159], v[188:191], v[120:123]
	v_mfma_f32_16x16x32_bf16 v[108:111], v[148:151], v[196:199], v[108:111]
	v_mfma_f32_16x16x32_bf16 v[104:107], v[156:159], v[196:199], v[104:107]
	v_mfma_f32_16x16x32_bf16 v[92:95], v[148:151], v[204:207], v[92:95]
	v_mfma_f32_16x16x32_bf16 v[88:91], v[156:159], v[204:207], v[88:91]
	v_mfma_f32_16x16x32_bf16 v[76:79], v[148:151], v[212:215], v[76:79]
	v_mfma_f32_16x16x32_bf16 v[72:75], v[156:159], v[212:215], v[72:75]
	s_setprio 0
	s_setprio 1
	v_mfma_f32_16x16x32_bf16 v[116:119], v[160:163], v[184:187], v[116:119]
	v_mfma_f32_16x16x32_bf16 v[112:115], v[168:171], v[184:187], v[112:115]
	v_mfma_f32_16x16x32_bf16 v[100:103], v[160:163], v[192:195], v[100:103]
	v_mfma_f32_16x16x32_bf16 v[96:99], v[168:171], v[192:195], v[96:99]
	v_mfma_f32_16x16x32_bf16 v[84:87], v[160:163], v[200:203], v[84:87]
	v_mfma_f32_16x16x32_bf16 v[80:83], v[168:171], v[200:203], v[80:83]
	v_mfma_f32_16x16x32_bf16 v[68:71], v[160:163], v[208:211], v[68:71]
	v_mfma_f32_16x16x32_bf16 v[64:67], v[168:171], v[208:211], v[64:67]
	v_mfma_f32_16x16x32_bf16 v[116:119], v[164:167], v[188:191], v[116:119]
	v_mfma_f32_16x16x32_bf16 v[112:115], v[172:175], v[188:191], v[112:115]
	v_mfma_f32_16x16x32_bf16 v[100:103], v[164:167], v[196:199], v[100:103]
	v_mfma_f32_16x16x32_bf16 v[96:99], v[172:175], v[196:199], v[96:99]
	s_setprio 2
	s_barrier
	v_mfma_f32_16x16x32_bf16 v[84:87], v[164:167], v[204:207], v[84:87]
	v_mfma_f32_16x16x32_bf16 v[80:83], v[172:175], v[204:207], v[80:83]
	v_mfma_f32_16x16x32_bf16 v[68:71], v[164:167], v[212:215], v[68:71]
	v_mfma_f32_16x16x32_bf16 v[64:67], v[172:175], v[212:215], v[64:67]
	s_setprio 0
	s_add_i32 s44, s74, s51
	v_lshl_add_u64 v[176:177], v[176:177], 0, s[22:23]
	s_mov_b32 m0, s44
	ds_read_b128 v[184:187], v181 offset:49152
	ds_read_b128 v[188:191], v181 offset:50176
	ds_read_b128 v[192:195], v181 offset:51200
	ds_read_b128 v[196:199], v181 offset:52224
	ds_read_b128 v[200:203], v181 offset:53248
	ds_read_b128 v[204:207], v181 offset:54272
	ds_read_b128 v[208:211], v181 offset:55296
	ds_read_b128 v[212:215], v181 offset:56320
	global_load_lds_dwordx4 v[176:177], off
	s_add_i32 m0, s44, 0x2000
	s_add_u32 s40, s40, 0x40080
	v_lshl_add_u64 v[176:177], v[216:217], 0, s[22:23]
	s_addc_u32 s41, s41, 0
	s_add_i32 s44, s75, s51
	global_load_lds_dwordx4 v[176:177], off
	v_lshl_add_u64 v[176:177], s[40:41], 0, v[130:131]
	s_mov_b32 m0, s44
	s_nop 0
	global_load_lds_dwordx4 v[176:177], off
	v_lshl_add_u64 v[176:177], s[40:41], 0, v[134:135]
	s_add_i32 m0, s44, 0x2000
	s_nop 0
	global_load_lds_dwordx4 v[176:177], off
	v_lshl_add_u64 v[176:177], v[218:219], 0, s[22:23]
	s_mov_b32 m0, s64
	s_nop 0
	global_load_lds_dwordx4 v[176:177], off
	v_lshl_add_u64 v[176:177], v[220:221], 0, s[22:23]
	s_mov_b32 m0, s65
	s_nop 0
	global_load_lds_dwordx4 v[176:177], off
	s_waitcnt vmcnt(8)
	s_waitcnt lgkmcnt(0)
	s_barrier
	s_setprio 1
	s_waitcnt lgkmcnt(0)
	v_mfma_f32_16x16x32_bf16 v[60:63], v[144:147], v[184:187], v[60:63]
	v_mfma_f32_16x16x32_bf16 v[56:59], v[152:155], v[184:187], v[56:59]
	v_mfma_f32_16x16x32_bf16 v[44:47], v[144:147], v[192:195], v[44:47]
	v_mfma_f32_16x16x32_bf16 v[40:43], v[152:155], v[192:195], v[40:43]
	v_mfma_f32_16x16x32_bf16 v[28:31], v[144:147], v[200:203], v[28:31]
	v_mfma_f32_16x16x32_bf16 v[24:27], v[152:155], v[200:203], v[24:27]
	v_mfma_f32_16x16x32_bf16 v[12:15], v[144:147], v[208:211], v[12:15]
	v_mfma_f32_16x16x32_bf16 v[8:11], v[152:155], v[208:211], v[8:11]
	v_mfma_f32_16x16x32_bf16 v[60:63], v[148:151], v[188:191], v[60:63]
	v_mfma_f32_16x16x32_bf16 v[56:59], v[156:159], v[188:191], v[56:59]
	v_mfma_f32_16x16x32_bf16 v[44:47], v[148:151], v[196:199], v[44:47]
	v_mfma_f32_16x16x32_bf16 v[40:43], v[156:159], v[196:199], v[40:43]
	v_mfma_f32_16x16x32_bf16 v[28:31], v[148:151], v[204:207], v[28:31]
	v_mfma_f32_16x16x32_bf16 v[24:27], v[156:159], v[204:207], v[24:27]
	v_mfma_f32_16x16x32_bf16 v[12:15], v[148:151], v[212:215], v[12:15]
	v_mfma_f32_16x16x32_bf16 v[8:11], v[156:159], v[212:215], v[8:11]
	s_setprio 0
	s_setprio 1
	v_mfma_f32_16x16x32_bf16 v[52:55], v[160:163], v[184:187], v[52:55]
	v_mfma_f32_16x16x32_bf16 v[48:51], v[168:171], v[184:187], v[48:51]
	v_mfma_f32_16x16x32_bf16 v[36:39], v[160:163], v[192:195], v[36:39]
	v_mfma_f32_16x16x32_bf16 v[32:35], v[168:171], v[192:195], v[32:35]
	v_mfma_f32_16x16x32_bf16 v[20:23], v[160:163], v[200:203], v[20:23]
	v_mfma_f32_16x16x32_bf16 v[16:19], v[168:171], v[200:203], v[16:19]
	v_mfma_f32_16x16x32_bf16 v[4:7], v[160:163], v[208:211], v[4:7]
	v_mfma_f32_16x16x32_bf16 v[0:3], v[168:171], v[208:211], v[0:3]
	v_mfma_f32_16x16x32_bf16 v[52:55], v[164:167], v[188:191], v[52:55]
	v_mfma_f32_16x16x32_bf16 v[48:51], v[172:175], v[188:191], v[48:51]
	v_mfma_f32_16x16x32_bf16 v[36:39], v[164:167], v[196:199], v[36:39]
	v_mfma_f32_16x16x32_bf16 v[32:35], v[172:175], v[196:199], v[32:35]
	s_setprio 2
	s_barrier
	v_mfma_f32_16x16x32_bf16 v[20:23], v[164:167], v[204:207], v[20:23]
	v_mfma_f32_16x16x32_bf16 v[16:19], v[172:175], v[204:207], v[16:19]
	v_mfma_f32_16x16x32_bf16 v[4:7], v[164:167], v[212:215], v[4:7]
	v_mfma_f32_16x16x32_bf16 v[0:3], v[172:175], v[212:215], v[0:3]
	s_setprio 0
	s_add_i32 s73, s73, 2
	s_add_u32 s6, s6, 0x100
	s_addc_u32 s7, s7, 0
	s_add_u32 s71, s71, 0x100
	s_addc_u32 s72, s72, 0
	s_cmp_gt_u32 s73, 13

.LBB0_1145:
	s_ashr_i32 s23, s22, 31
	s_lshl_b64 s[26:27], s[22:23], 19
	s_add_u32 s26, s45, s26
	s_addc_u32 s27, s46, s27
	s_and_b64 s[28:29], s[4:5], exec
	s_cselect_b32 s23, s27, s39
	s_cselect_b32 s31, s26, s38
	s_ashr_i32 s25, s24, 31
	s_lshl_b64 s[28:29], s[24:25], 19
	s_add_u32 s28, s47, s28
	s_addc_u32 s29, s48, s29
	s_and_b64 s[42:43], s[4:5], exec
	s_cselect_b32 s25, s29, s41
	s_cselect_b32 s37, s28, s40
	s_add_u32 s38, s38, 0x40080
	s_addc_u32 s39, s39, 0
	s_add_u32 s64, s40, 0x100
	s_addc_u32 s65, s41, 0
	s_mov_b32 s66, -2
	ds_read_b128 v[120:123], v233
	ds_read_b128 v[132:135], v233 offset:1024
	ds_read_b128 v[136:139], v233 offset:2048
	ds_read_b128 v[140:143], v233 offset:3072
	ds_read_b128 v[144:147], v234
	ds_read_b128 v[148:151], v234 offset:1024
	ds_read_b128 v[152:155], v234 offset:2048
	ds_read_b128 v[156:159], v234 offset:3072
	s_add_u32 s40, s38, 0xfffc0080
	s_addc_u32 s41, s39, -1
	s_cmp_eq_u32 s66, 12
	s_cselect_b32 s43, s23, s41
	s_cselect_b32 s42, s31, s40
	s_cselect_b32 s41, s25, s65
	s_cselect_b32 s40, s37, s64
	v_lshl_add_u64 v[208:209], s[38:39], 0, v[192:193]
	s_add_i32 m0, s50, 0xc000
	ds_read_b128 v[160:163], v235
	ds_read_b128 v[164:167], v235 offset:1024
	ds_read_b128 v[168:171], v235 offset:2048
	ds_read_b128 v[172:175], v235 offset:3072
	ds_read_b128 v[176:179], v235 offset:4096
	ds_read_b128 v[180:183], v235 offset:5120
	ds_read_b128 v[200:203], v235 offset:6144
	ds_read_b128 v[204:207], v235 offset:7168
	global_load_lds_dwordx4 v[208:209], off
	v_lshl_add_u64 v[208:209], s[38:39], 0, v[194:195]
	s_add_i32 m0, s50, 0xe000
	s_nop 0
	global_load_lds_dwordx4 v[208:209], off
	s_waitcnt vmcnt(8)
	s_waitcnt lgkmcnt(0)
	s_barrier
	s_setprio 1
	s_waitcnt lgkmcnt(0)
	v_mfma_f32_16x16x32_bf16 v[128:131], v[120:123], v[160:163], 0
	v_mfma_f32_16x16x32_bf16 v[124:127], v[136:139], v[160:163], 0
	v_mfma_f32_16x16x32_bf16 v[108:111], v[120:123], v[168:171], 0
	v_mfma_f32_16x16x32_bf16 v[104:107], v[136:139], v[168:171], 0
	v_mfma_f32_16x16x32_bf16 v[92:95], v[120:123], v[176:179], 0
	v_mfma_f32_16x16x32_bf16 v[88:91], v[136:139], v[176:179], 0
	v_mfma_f32_16x16x32_bf16 v[76:79], v[120:123], v[200:203], 0
	v_mfma_f32_16x16x32_bf16 v[72:75], v[136:139], v[200:203], 0
	v_mfma_f32_16x16x32_bf16 v[128:131], v[132:135], v[164:167], v[128:131]
	v_mfma_f32_16x16x32_bf16 v[124:127], v[140:143], v[164:167], v[124:127]
	v_mfma_f32_16x16x32_bf16 v[108:111], v[132:135], v[172:175], v[108:111]
	v_mfma_f32_16x16x32_bf16 v[104:107], v[140:143], v[172:175], v[104:107]
	v_mfma_f32_16x16x32_bf16 v[92:95], v[132:135], v[180:183], v[92:95]
	v_mfma_f32_16x16x32_bf16 v[88:91], v[140:143], v[180:183], v[88:91]
	v_mfma_f32_16x16x32_bf16 v[76:79], v[132:135], v[204:207], v[76:79]
	v_mfma_f32_16x16x32_bf16 v[72:75], v[140:143], v[204:207], v[72:75]
	s_setprio 0
	s_setprio 1
	v_mfma_f32_16x16x32_bf16 v[116:119], v[144:147], v[160:163], 0
	v_mfma_f32_16x16x32_bf16 v[112:115], v[152:155], v[160:163], 0
	v_mfma_f32_16x16x32_bf16 v[100:103], v[144:147], v[168:171], 0
	v_mfma_f32_16x16x32_bf16 v[96:99], v[152:155], v[168:171], 0
	v_mfma_f32_16x16x32_bf16 v[84:87], v[144:147], v[176:179], 0
	v_mfma_f32_16x16x32_bf16 v[80:83], v[152:155], v[176:179], 0
	v_mfma_f32_16x16x32_bf16 v[68:71], v[144:147], v[200:203], 0
	v_mfma_f32_16x16x32_bf16 v[64:67], v[152:155], v[200:203], 0
	v_mfma_f32_16x16x32_bf16 v[116:119], v[148:151], v[164:167], v[116:119]
	v_mfma_f32_16x16x32_bf16 v[112:115], v[156:159], v[164:167], v[112:115]
	v_mfma_f32_16x16x32_bf16 v[100:103], v[148:151], v[172:175], v[100:103]
	v_mfma_f32_16x16x32_bf16 v[96:99], v[156:159], v[172:175], v[96:99]
	s_setprio 2
	s_barrier
	v_mfma_f32_16x16x32_bf16 v[84:87], v[148:151], v[180:183], v[84:87]
	v_mfma_f32_16x16x32_bf16 v[80:83], v[156:159], v[180:183], v[80:83]
	v_mfma_f32_16x16x32_bf16 v[68:71], v[148:151], v[204:207], v[68:71]
	v_mfma_f32_16x16x32_bf16 v[64:67], v[156:159], v[204:207], v[64:67]
	s_setprio 0
	s_add_i32 s67, s62, s49
	v_lshl_add_u64 v[208:209], s[40:41], 0, v[186:187]
	s_mov_b32 m0, s67
	ds_read_b128 v[160:163], v235 offset:16384
	ds_read_b128 v[164:167], v235 offset:17408
	ds_read_b128 v[168:171], v235 offset:18432
	ds_read_b128 v[172:175], v235 offset:19456
	ds_read_b128 v[176:179], v235 offset:20480
	ds_read_b128 v[180:183], v235 offset:21504
	ds_read_b128 v[200:203], v235 offset:22528
	ds_read_b128 v[204:207], v235 offset:23552
	global_load_lds_dwordx4 v[208:209], off
	s_add_i32 m0, s67, 0x2000
	s_add_u32 s68, s40, 0x40000
	v_lshl_add_u64 v[210:211], s[40:41], 0, v[190:191]
	s_addc_u32 s69, s41, 0
	s_add_i32 s67, s63, s49
	global_load_lds_dwordx4 v[210:211], off
	v_lshl_add_u64 v[212:213], s[68:69], 0, v[186:187]
	s_mov_b32 m0, s67
	v_lshl_add_u64 v[214:215], s[42:43], 0, v[188:189]
	global_load_lds_dwordx4 v[212:213], off
	v_lshl_add_u64 v[212:213], s[68:69], 0, v[190:191]
	s_add_i32 m0, s67, 0x2000
	s_nop 0
	global_load_lds_dwordx4 v[212:213], off
	v_lshl_add_u64 v[212:213], s[42:43], 0, v[184:185]
	s_mov_b32 m0, s50
	s_nop 0
	global_load_lds_dwordx4 v[212:213], off
	s_mov_b32 m0, s51
	s_nop 0
	global_load_lds_dwordx4 v[214:215], off
	s_waitcnt vmcnt(8)
	s_waitcnt lgkmcnt(0)
	s_barrier
	s_setprio 1
	s_waitcnt lgkmcnt(0)
	v_mfma_f32_16x16x32_bf16 v[60:63], v[120:123], v[160:163], 0
	v_mfma_f32_16x16x32_bf16 v[56:59], v[136:139], v[160:163], 0
	v_mfma_f32_16x16x32_bf16 v[44:47], v[120:123], v[168:171], 0
	v_mfma_f32_16x16x32_bf16 v[40:43], v[136:139], v[168:171], 0
	v_mfma_f32_16x16x32_bf16 v[28:31], v[120:123], v[176:179], 0
	v_mfma_f32_16x16x32_bf16 v[24:27], v[136:139], v[176:179], 0
	v_mfma_f32_16x16x32_bf16 v[12:15], v[120:123], v[200:203], 0
	v_mfma_f32_16x16x32_bf16 v[8:11], v[136:139], v[200:203], 0
	v_mfma_f32_16x16x32_bf16 v[60:63], v[132:135], v[164:167], v[60:63]
	v_mfma_f32_16x16x32_bf16 v[56:59], v[140:143], v[164:167], v[56:59]
	v_mfma_f32_16x16x32_bf16 v[44:47], v[132:135], v[172:175], v[44:47]
	v_mfma_f32_16x16x32_bf16 v[40:43], v[140:143], v[172:175], v[40:43]
	v_mfma_f32_16x16x32_bf16 v[28:31], v[132:135], v[180:183], v[28:31]
	v_mfma_f32_16x16x32_bf16 v[24:27], v[140:143], v[180:183], v[24:27]
	v_mfma_f32_16x16x32_bf16 v[12:15], v[132:135], v[204:207], v[12:15]
	v_mfma_f32_16x16x32_bf16 v[8:11], v[140:143], v[204:207], v[8:11]
	s_setprio 0
	s_setprio 1
	v_mfma_f32_16x16x32_bf16 v[52:55], v[144:147], v[160:163], 0
	v_mfma_f32_16x16x32_bf16 v[48:51], v[152:155], v[160:163], 0
	v_mfma_f32_16x16x32_bf16 v[36:39], v[144:147], v[168:171], 0
	v_mfma_f32_16x16x32_bf16 v[32:35], v[152:155], v[168:171], 0
	v_mfma_f32_16x16x32_bf16 v[20:23], v[144:147], v[176:179], 0
	v_mfma_f32_16x16x32_bf16 v[16:19], v[152:155], v[176:179], 0
	v_mfma_f32_16x16x32_bf16 v[4:7], v[144:147], v[200:203], 0
	v_mfma_f32_16x16x32_bf16 v[0:3], v[152:155], v[200:203], 0
	v_mfma_f32_16x16x32_bf16 v[52:55], v[148:151], v[164:167], v[52:55]
	v_mfma_f32_16x16x32_bf16 v[48:51], v[156:159], v[164:167], v[48:51]
	v_mfma_f32_16x16x32_bf16 v[36:39], v[148:151], v[172:175], v[36:39]
	v_mfma_f32_16x16x32_bf16 v[32:35], v[156:159], v[172:175], v[32:35]
	s_setprio 2
	s_barrier
	v_mfma_f32_16x16x32_bf16 v[20:23], v[148:151], v[180:183], v[20:23]
	v_mfma_f32_16x16x32_bf16 v[16:19], v[156:159], v[180:183], v[16:19]
	v_mfma_f32_16x16x32_bf16 v[4:7], v[148:151], v[204:207], v[4:7]
	v_mfma_f32_16x16x32_bf16 v[0:3], v[156:159], v[204:207], v[0:3]
	s_setprio 0
	s_add_i32 s67, 0, 0x18000
	s_add_i32 s68, 0, 0x1c000
	v_add_u32_e32 v140, s67, v232
	v_add_u32_e32 v156, s68, v232
	ds_read_b128 v[120:123], v140
	ds_read_b128 v[132:135], v140 offset:1024
	ds_read_b128 v[136:139], v140 offset:2048
	ds_read_b128 v[140:143], v140 offset:3072
	ds_read_b128 v[144:147], v156
	ds_read_b128 v[148:151], v156 offset:1024
	ds_read_b128 v[152:155], v156 offset:2048
	ds_read_b128 v[156:159], v156 offset:3072
	s_add_u32 s42, s42, 0x40000
	s_addc_u32 s43, s43, 0
	s_mov_b32 m0, s54
	v_lshl_add_u64 v[216:217], s[42:43], 0, v[184:185]
	ds_read_b128 v[160:163], v235 offset:32768
	ds_read_b128 v[164:167], v235 offset:33792
	ds_read_b128 v[168:171], v235 offset:34816
	ds_read_b128 v[172:175], v235 offset:35840
	ds_read_b128 v[176:179], v235 offset:36864
	ds_read_b128 v[180:183], v235 offset:37888
	ds_read_b128 v[200:203], v235 offset:38912
	ds_read_b128 v[204:207], v235 offset:39936
	global_load_lds_dwordx4 v[216:217], off
	v_lshl_add_u64 v[216:217], s[42:43], 0, v[188:189]
	s_mov_b32 m0, s55
	s_nop 0
	global_load_lds_dwordx4 v[216:217], off
	s_waitcnt vmcnt(8)
	s_waitcnt lgkmcnt(0)
	s_barrier
	s_setprio 1
	s_waitcnt lgkmcnt(0)
	v_mfma_f32_16x16x32_bf16 v[128:131], v[120:123], v[160:163], v[128:131]
	v_mfma_f32_16x16x32_bf16 v[124:127], v[136:139], v[160:163], v[124:127]
	v_mfma_f32_16x16x32_bf16 v[108:111], v[120:123], v[168:171], v[108:111]
	v_mfma_f32_16x16x32_bf16 v[104:107], v[136:139], v[168:171], v[104:107]
	v_mfma_f32_16x16x32_bf16 v[92:95], v[120:123], v[176:179], v[92:95]
	v_mfma_f32_16x16x32_bf16 v[88:91], v[136:139], v[176:179], v[88:91]
	v_mfma_f32_16x16x32_bf16 v[76:79], v[120:123], v[200:203], v[76:79]
	v_mfma_f32_16x16x32_bf16 v[72:75], v[136:139], v[200:203], v[72:75]
	v_mfma_f32_16x16x32_bf16 v[128:131], v[132:135], v[164:167], v[128:131]
	v_mfma_f32_16x16x32_bf16 v[124:127], v[140:143], v[164:167], v[124:127]
	v_mfma_f32_16x16x32_bf16 v[108:111], v[132:135], v[172:175], v[108:111]
	v_mfma_f32_16x16x32_bf16 v[104:107], v[140:143], v[172:175], v[104:107]
	v_mfma_f32_16x16x32_bf16 v[92:95], v[132:135], v[180:183], v[92:95]
	v_mfma_f32_16x16x32_bf16 v[88:91], v[140:143], v[180:183], v[88:91]
	v_mfma_f32_16x16x32_bf16 v[76:79], v[132:135], v[204:207], v[76:79]
	v_mfma_f32_16x16x32_bf16 v[72:75], v[140:143], v[204:207], v[72:75]
	s_setprio 0
	s_setprio 1
	v_mfma_f32_16x16x32_bf16 v[116:119], v[144:147], v[160:163], v[116:119]
	v_mfma_f32_16x16x32_bf16 v[112:115], v[152:155], v[160:163], v[112:115]
	v_mfma_f32_16x16x32_bf16 v[100:103], v[144:147], v[168:171], v[100:103]
	v_mfma_f32_16x16x32_bf16 v[96:99], v[152:155], v[168:171], v[96:99]
	v_mfma_f32_16x16x32_bf16 v[84:87], v[144:147], v[176:179], v[84:87]
	v_mfma_f32_16x16x32_bf16 v[80:83], v[152:155], v[176:179], v[80:83]
	v_mfma_f32_16x16x32_bf16 v[68:71], v[144:147], v[200:203], v[68:71]
	v_mfma_f32_16x16x32_bf16 v[64:67], v[152:155], v[200:203], v[64:67]
	v_mfma_f32_16x16x32_bf16 v[116:119], v[148:151], v[164:167], v[116:119]
	v_mfma_f32_16x16x32_bf16 v[112:115], v[156:159], v[164:167], v[112:115]
	v_mfma_f32_16x16x32_bf16 v[100:103], v[148:151], v[172:175], v[100:103]
	v_mfma_f32_16x16x32_bf16 v[96:99], v[156:159], v[172:175], v[96:99]
	s_setprio 2
	s_barrier
	v_mfma_f32_16x16x32_bf16 v[84:87], v[148:151], v[180:183], v[84:87]
	v_mfma_f32_16x16x32_bf16 v[80:83], v[156:159], v[180:183], v[80:83]
	v_mfma_f32_16x16x32_bf16 v[68:71], v[148:151], v[204:207], v[68:71]
	v_mfma_f32_16x16x32_bf16 v[64:67], v[156:159], v[204:207], v[64:67]
	s_setprio 0
	s_add_i32 s42, s67, s49
	v_lshl_add_u64 v[208:209], v[208:209], 0, s[18:19]
	s_mov_b32 m0, s42
	ds_read_b128 v[160:163], v235 offset:49152
	ds_read_b128 v[164:167], v235 offset:50176
	ds_read_b128 v[168:171], v235 offset:51200
	ds_read_b128 v[172:175], v235 offset:52224
	ds_read_b128 v[176:179], v235 offset:53248
	ds_read_b128 v[180:183], v235 offset:54272
	ds_read_b128 v[200:203], v235 offset:55296
	ds_read_b128 v[204:207], v235 offset:56320
	global_load_lds_dwordx4 v[208:209], off
	s_add_i32 m0, s42, 0x2000
	s_add_u32 s40, s40, 0x40080
	v_lshl_add_u64 v[208:209], v[210:211], 0, s[18:19]
	s_addc_u32 s41, s41, 0
	s_add_i32 s42, s68, s49
	global_load_lds_dwordx4 v[208:209], off
	v_lshl_add_u64 v[208:209], s[40:41], 0, v[186:187]
	s_mov_b32 m0, s42
	s_nop 0
	global_load_lds_dwordx4 v[208:209], off
	v_lshl_add_u64 v[208:209], s[40:41], 0, v[190:191]
	s_add_i32 m0, s42, 0x2000
	s_nop 0
	global_load_lds_dwordx4 v[208:209], off
	v_lshl_add_u64 v[208:209], v[212:213], 0, s[18:19]
	s_mov_b32 m0, s57
	s_nop 0
	global_load_lds_dwordx4 v[208:209], off
	v_lshl_add_u64 v[208:209], v[214:215], 0, s[18:19]
	s_mov_b32 m0, s58
	s_nop 0
	global_load_lds_dwordx4 v[208:209], off
	s_waitcnt vmcnt(8)
	s_waitcnt lgkmcnt(0)
	s_barrier
	s_setprio 1
	s_waitcnt lgkmcnt(0)
	v_mfma_f32_16x16x32_bf16 v[60:63], v[120:123], v[160:163], v[60:63]
	v_mfma_f32_16x16x32_bf16 v[56:59], v[136:139], v[160:163], v[56:59]
	v_mfma_f32_16x16x32_bf16 v[44:47], v[120:123], v[168:171], v[44:47]
	v_mfma_f32_16x16x32_bf16 v[40:43], v[136:139], v[168:171], v[40:43]
	v_mfma_f32_16x16x32_bf16 v[28:31], v[120:123], v[176:179], v[28:31]
	v_mfma_f32_16x16x32_bf16 v[24:27], v[136:139], v[176:179], v[24:27]
	v_mfma_f32_16x16x32_bf16 v[12:15], v[120:123], v[200:203], v[12:15]
	v_mfma_f32_16x16x32_bf16 v[8:11], v[136:139], v[200:203], v[8:11]
	v_mfma_f32_16x16x32_bf16 v[60:63], v[132:135], v[164:167], v[60:63]
	v_mfma_f32_16x16x32_bf16 v[56:59], v[140:143], v[164:167], v[56:59]
	v_mfma_f32_16x16x32_bf16 v[44:47], v[132:135], v[172:175], v[44:47]
	v_mfma_f32_16x16x32_bf16 v[40:43], v[140:143], v[172:175], v[40:43]
	v_mfma_f32_16x16x32_bf16 v[28:31], v[132:135], v[180:183], v[28:31]
	v_mfma_f32_16x16x32_bf16 v[24:27], v[140:143], v[180:183], v[24:27]
	v_mfma_f32_16x16x32_bf16 v[12:15], v[132:135], v[204:207], v[12:15]
	v_mfma_f32_16x16x32_bf16 v[8:11], v[140:143], v[204:207], v[8:11]
	s_setprio 0
	s_setprio 1
	v_mfma_f32_16x16x32_bf16 v[52:55], v[144:147], v[160:163], v[52:55]
	v_mfma_f32_16x16x32_bf16 v[48:51], v[152:155], v[160:163], v[48:51]
	v_mfma_f32_16x16x32_bf16 v[36:39], v[144:147], v[168:171], v[36:39]
	v_mfma_f32_16x16x32_bf16 v[32:35], v[152:155], v[168:171], v[32:35]
	v_mfma_f32_16x16x32_bf16 v[20:23], v[144:147], v[176:179], v[20:23]
	v_mfma_f32_16x16x32_bf16 v[16:19], v[152:155], v[176:179], v[16:19]
	v_mfma_f32_16x16x32_bf16 v[4:7], v[144:147], v[200:203], v[4:7]
	v_mfma_f32_16x16x32_bf16 v[0:3], v[152:155], v[200:203], v[0:3]
	v_mfma_f32_16x16x32_bf16 v[52:55], v[148:151], v[164:167], v[52:55]
	v_mfma_f32_16x16x32_bf16 v[48:51], v[156:159], v[164:167], v[48:51]
	v_mfma_f32_16x16x32_bf16 v[36:39], v[148:151], v[172:175], v[36:39]
	v_mfma_f32_16x16x32_bf16 v[32:35], v[156:159], v[172:175], v[32:35]
	s_setprio 2
	s_barrier
	v_mfma_f32_16x16x32_bf16 v[20:23], v[148:151], v[180:183], v[20:23]
	v_mfma_f32_16x16x32_bf16 v[16:19], v[156:159], v[180:183], v[16:19]
	v_mfma_f32_16x16x32_bf16 v[4:7], v[148:151], v[204:207], v[4:7]
	v_mfma_f32_16x16x32_bf16 v[0:3], v[156:159], v[204:207], v[0:3]
	s_setprio 0
	s_add_i32 s66, s66, 2
	s_add_u32 s38, s38, 0x100
	s_addc_u32 s39, s39, 0
	s_add_u32 s64, s64, 0x100
	s_addc_u32 s65, s65, 0
	s_cmp_gt_u32 s66, 13

.LBB0_1309:
	s_add_u32 s51, s26, 0x100
	s_addc_u32 s52, s27, 0
	s_mov_b32 s53, -2
	ds_read_b128 v[128:131], v197
	ds_read_b128 v[132:135], v197 offset:1024
	ds_read_b128 v[136:139], v197 offset:2048
	ds_read_b128 v[140:143], v197 offset:3072
	ds_read_b128 v[144:147], v198
	ds_read_b128 v[148:151], v198 offset:1024
	ds_read_b128 v[152:155], v198 offset:2048
	ds_read_b128 v[156:159], v198 offset:3072
	s_add_u32 s4, s24, 0x100
	s_addc_u32 s5, s25, 0
	s_cmp_eq_u32 s53, 40
	s_cselect_b32 s29, s21, s5
	s_cselect_b32 s28, s20, s4
	s_cselect_b32 s27, s23, s52
	s_cselect_b32 s26, s22, s51
	v_lshl_add_u64 v[212:213], s[24:25], 0, v[172:173]
	s_add_i32 m0, s36, 0xc000
	ds_read_b128 v[160:163], v199
	ds_read_b128 v[180:183], v199 offset:1024
	ds_read_b128 v[184:187], v199 offset:2048
	ds_read_b128 v[188:191], v199 offset:3072
	ds_read_b128 v[192:195], v199 offset:4096
	ds_read_b128 v[200:203], v199 offset:5120
	ds_read_b128 v[204:207], v199 offset:6144
	ds_read_b128 v[208:211], v199 offset:7168
	global_load_lds_dwordx4 v[212:213], off
	v_lshl_add_u64 v[212:213], s[24:25], 0, v[174:175]
	s_add_i32 m0, s36, 0xe000
	s_nop 0
	global_load_lds_dwordx4 v[212:213], off
	s_waitcnt vmcnt(8)
	s_waitcnt lgkmcnt(0)
	s_barrier
	s_setprio 1
	s_waitcnt lgkmcnt(0)
	v_mfma_f32_16x16x32_bf16 v[124:127], v[128:131], v[160:163], 0
	v_mfma_f32_16x16x32_bf16 v[120:123], v[136:139], v[160:163], 0
	v_mfma_f32_16x16x32_bf16 v[116:119], v[128:131], v[184:187], 0
	v_mfma_f32_16x16x32_bf16 v[108:111], v[136:139], v[184:187], 0
	v_mfma_f32_16x16x32_bf16 v[88:91], v[128:131], v[192:195], 0
	v_mfma_f32_16x16x32_bf16 v[100:103], v[136:139], v[192:195], 0
	v_mfma_f32_16x16x32_bf16 v[72:75], v[128:131], v[204:207], 0
	v_mfma_f32_16x16x32_bf16 v[76:79], v[136:139], v[204:207], 0
	v_mfma_f32_16x16x32_bf16 v[124:127], v[132:135], v[180:183], v[124:127]
	v_mfma_f32_16x16x32_bf16 v[120:123], v[140:143], v[180:183], v[120:123]
	v_mfma_f32_16x16x32_bf16 v[116:119], v[132:135], v[188:191], v[116:119]
	v_mfma_f32_16x16x32_bf16 v[108:111], v[140:143], v[188:191], v[108:111]
	v_mfma_f32_16x16x32_bf16 v[88:91], v[132:135], v[200:203], v[88:91]
	v_mfma_f32_16x16x32_bf16 v[100:103], v[140:143], v[200:203], v[100:103]
	v_mfma_f32_16x16x32_bf16 v[72:75], v[132:135], v[208:211], v[72:75]
	v_mfma_f32_16x16x32_bf16 v[76:79], v[140:143], v[208:211], v[76:79]
	s_setprio 0
	s_setprio 1
	v_mfma_f32_16x16x32_bf16 v[112:115], v[144:147], v[160:163], 0
	v_mfma_f32_16x16x32_bf16 v[104:107], v[152:155], v[160:163], 0
	v_mfma_f32_16x16x32_bf16 v[96:99], v[144:147], v[184:187], 0
	v_mfma_f32_16x16x32_bf16 v[92:95], v[152:155], v[184:187], 0
	v_mfma_f32_16x16x32_bf16 v[80:83], v[144:147], v[192:195], 0
	v_mfma_f32_16x16x32_bf16 v[84:87], v[152:155], v[192:195], 0
	v_mfma_f32_16x16x32_bf16 v[64:67], v[144:147], v[204:207], 0
	v_mfma_f32_16x16x32_bf16 v[68:71], v[152:155], v[204:207], 0
	v_mfma_f32_16x16x32_bf16 v[112:115], v[148:151], v[180:183], v[112:115]
	v_mfma_f32_16x16x32_bf16 v[104:107], v[156:159], v[180:183], v[104:107]
	v_mfma_f32_16x16x32_bf16 v[96:99], v[148:151], v[188:191], v[96:99]
	v_mfma_f32_16x16x32_bf16 v[92:95], v[156:159], v[188:191], v[92:95]
	s_setprio 2
	s_barrier
	v_mfma_f32_16x16x32_bf16 v[80:83], v[148:151], v[200:203], v[80:83]
	v_mfma_f32_16x16x32_bf16 v[84:87], v[156:159], v[200:203], v[84:87]
	v_mfma_f32_16x16x32_bf16 v[64:67], v[148:151], v[208:211], v[64:67]
	v_mfma_f32_16x16x32_bf16 v[68:71], v[156:159], v[208:211], v[68:71]
	s_setprio 0
	s_add_i32 s24, s45, s35
	v_lshl_add_u64 v[212:213], s[26:27], 0, v[166:167]
	s_mov_b32 m0, s24
	ds_read_b128 v[160:163], v199 offset:16384
	ds_read_b128 v[180:183], v199 offset:17408
	ds_read_b128 v[184:187], v199 offset:18432
	ds_read_b128 v[188:191], v199 offset:19456
	ds_read_b128 v[192:195], v199 offset:20480
	ds_read_b128 v[200:203], v199 offset:21504
	ds_read_b128 v[204:207], v199 offset:22528
	ds_read_b128 v[208:211], v199 offset:23552
	global_load_lds_dwordx4 v[212:213], off
	s_add_i32 m0, s24, 0x2000
	s_add_u32 s24, s26, 0xb0000
	v_lshl_add_u64 v[214:215], s[26:27], 0, v[170:171]
	s_addc_u32 s25, s27, 0
	s_add_i32 s54, s46, s35
	global_load_lds_dwordx4 v[214:215], off
	v_lshl_add_u64 v[216:217], s[24:25], 0, v[166:167]
	s_mov_b32 m0, s54
	v_lshl_add_u64 v[218:219], s[28:29], 0, v[168:169]
	global_load_lds_dwordx4 v[216:217], off
	v_lshl_add_u64 v[216:217], s[24:25], 0, v[170:171]
	s_add_i32 m0, s54, 0x2000
	s_nop 0
	global_load_lds_dwordx4 v[216:217], off
	v_lshl_add_u64 v[216:217], s[28:29], 0, v[164:165]
	s_mov_b32 m0, s36
	s_nop 0
	global_load_lds_dwordx4 v[216:217], off
	s_mov_b32 m0, s37
	s_nop 0
	global_load_lds_dwordx4 v[218:219], off
	s_waitcnt vmcnt(8)
	s_waitcnt lgkmcnt(0)
	s_barrier
	s_setprio 1
	s_waitcnt lgkmcnt(0)
	v_mfma_f32_16x16x32_bf16 v[56:59], v[128:131], v[160:163], 0
	v_mfma_f32_16x16x32_bf16 v[60:63], v[136:139], v[160:163], 0
	v_mfma_f32_16x16x32_bf16 v[40:43], v[128:131], v[184:187], 0
	v_mfma_f32_16x16x32_bf16 v[44:47], v[136:139], v[184:187], 0
	v_mfma_f32_16x16x32_bf16 v[24:27], v[128:131], v[192:195], 0
	v_mfma_f32_16x16x32_bf16 v[28:31], v[136:139], v[192:195], 0
	v_mfma_f32_16x16x32_bf16 v[8:11], v[128:131], v[204:207], 0
	v_mfma_f32_16x16x32_bf16 v[12:15], v[136:139], v[204:207], 0
	v_mfma_f32_16x16x32_bf16 v[56:59], v[132:135], v[180:183], v[56:59]
	v_mfma_f32_16x16x32_bf16 v[60:63], v[140:143], v[180:183], v[60:63]
	v_mfma_f32_16x16x32_bf16 v[40:43], v[132:135], v[188:191], v[40:43]
	v_mfma_f32_16x16x32_bf16 v[44:47], v[140:143], v[188:191], v[44:47]
	v_mfma_f32_16x16x32_bf16 v[24:27], v[132:135], v[200:203], v[24:27]
	v_mfma_f32_16x16x32_bf16 v[28:31], v[140:143], v[200:203], v[28:31]
	v_mfma_f32_16x16x32_bf16 v[8:11], v[132:135], v[208:211], v[8:11]
	v_mfma_f32_16x16x32_bf16 v[12:15], v[140:143], v[208:211], v[12:15]
	s_setprio 0
	s_setprio 1
	v_mfma_f32_16x16x32_bf16 v[48:51], v[144:147], v[160:163], 0
	v_mfma_f32_16x16x32_bf16 v[52:55], v[152:155], v[160:163], 0
	v_mfma_f32_16x16x32_bf16 v[32:35], v[144:147], v[184:187], 0
	v_mfma_f32_16x16x32_bf16 v[36:39], v[152:155], v[184:187], 0
	v_mfma_f32_16x16x32_bf16 v[16:19], v[144:147], v[192:195], 0
	v_mfma_f32_16x16x32_bf16 v[20:23], v[152:155], v[192:195], 0
	v_mfma_f32_16x16x32_bf16 v[0:3], v[144:147], v[204:207], 0
	v_mfma_f32_16x16x32_bf16 v[4:7], v[152:155], v[204:207], 0
	v_mfma_f32_16x16x32_bf16 v[48:51], v[148:151], v[180:183], v[48:51]
	v_mfma_f32_16x16x32_bf16 v[52:55], v[156:159], v[180:183], v[52:55]
	v_mfma_f32_16x16x32_bf16 v[32:35], v[148:151], v[188:191], v[32:35]
	v_mfma_f32_16x16x32_bf16 v[36:39], v[156:159], v[188:191], v[36:39]
	s_setprio 2
	s_barrier
	v_mfma_f32_16x16x32_bf16 v[16:19], v[148:151], v[200:203], v[16:19]
	v_mfma_f32_16x16x32_bf16 v[20:23], v[156:159], v[200:203], v[20:23]
	v_mfma_f32_16x16x32_bf16 v[0:3], v[148:151], v[208:211], v[0:3]
	v_mfma_f32_16x16x32_bf16 v[4:7], v[156:159], v[208:211], v[4:7]
	s_setprio 0
	s_add_i32 s54, 0, 0x18000
	s_add_i32 s55, 0, 0x1c000
	v_add_u32_e32 v140, s54, v196
	v_add_u32_e32 v156, s55, v196
	ds_read_b128 v[128:131], v140
	ds_read_b128 v[132:135], v140 offset:1024
	ds_read_b128 v[136:139], v140 offset:2048
	ds_read_b128 v[140:143], v140 offset:3072
	ds_read_b128 v[144:147], v156
	ds_read_b128 v[148:151], v156 offset:1024
	ds_read_b128 v[152:155], v156 offset:2048
	ds_read_b128 v[156:159], v156 offset:3072
	s_add_u32 s24, s28, 0xb0000
	s_addc_u32 s25, s29, 0
	s_mov_b32 m0, s38
	v_lshl_add_u64 v[220:221], s[24:25], 0, v[164:165]
	ds_read_b128 v[160:163], v199 offset:32768
	ds_read_b128 v[180:183], v199 offset:33792
	ds_read_b128 v[184:187], v199 offset:34816
	ds_read_b128 v[188:191], v199 offset:35840
	ds_read_b128 v[192:195], v199 offset:36864
	ds_read_b128 v[200:203], v199 offset:37888
	ds_read_b128 v[204:207], v199 offset:38912
	ds_read_b128 v[208:211], v199 offset:39936
	global_load_lds_dwordx4 v[220:221], off
	v_lshl_add_u64 v[220:221], s[24:25], 0, v[168:169]
	s_mov_b32 m0, s39
	s_nop 0
	global_load_lds_dwordx4 v[220:221], off
	s_waitcnt vmcnt(8)
	s_waitcnt lgkmcnt(0)
	s_barrier
	s_setprio 1
	s_waitcnt lgkmcnt(0)
	v_mfma_f32_16x16x32_bf16 v[124:127], v[128:131], v[160:163], v[124:127]
	v_mfma_f32_16x16x32_bf16 v[120:123], v[136:139], v[160:163], v[120:123]
	v_mfma_f32_16x16x32_bf16 v[116:119], v[128:131], v[184:187], v[116:119]
	v_mfma_f32_16x16x32_bf16 v[108:111], v[136:139], v[184:187], v[108:111]
	v_mfma_f32_16x16x32_bf16 v[88:91], v[128:131], v[192:195], v[88:91]
	v_mfma_f32_16x16x32_bf16 v[100:103], v[136:139], v[192:195], v[100:103]
	v_mfma_f32_16x16x32_bf16 v[72:75], v[128:131], v[204:207], v[72:75]
	v_mfma_f32_16x16x32_bf16 v[76:79], v[136:139], v[204:207], v[76:79]
	v_mfma_f32_16x16x32_bf16 v[124:127], v[132:135], v[180:183], v[124:127]
	v_mfma_f32_16x16x32_bf16 v[120:123], v[140:143], v[180:183], v[120:123]
	v_mfma_f32_16x16x32_bf16 v[116:119], v[132:135], v[188:191], v[116:119]
	v_mfma_f32_16x16x32_bf16 v[108:111], v[140:143], v[188:191], v[108:111]
	v_mfma_f32_16x16x32_bf16 v[88:91], v[132:135], v[200:203], v[88:91]
	v_mfma_f32_16x16x32_bf16 v[100:103], v[140:143], v[200:203], v[100:103]
	v_mfma_f32_16x16x32_bf16 v[72:75], v[132:135], v[208:211], v[72:75]
	v_mfma_f32_16x16x32_bf16 v[76:79], v[140:143], v[208:211], v[76:79]
	s_setprio 0
	s_setprio 1
	v_mfma_f32_16x16x32_bf16 v[112:115], v[144:147], v[160:163], v[112:115]
	v_mfma_f32_16x16x32_bf16 v[104:107], v[152:155], v[160:163], v[104:107]
	v_mfma_f32_16x16x32_bf16 v[96:99], v[144:147], v[184:187], v[96:99]
	v_mfma_f32_16x16x32_bf16 v[92:95], v[152:155], v[184:187], v[92:95]
	v_mfma_f32_16x16x32_bf16 v[80:83], v[144:147], v[192:195], v[80:83]
	v_mfma_f32_16x16x32_bf16 v[84:87], v[152:155], v[192:195], v[84:87]
	v_mfma_f32_16x16x32_bf16 v[64:67], v[144:147], v[204:207], v[64:67]
	v_mfma_f32_16x16x32_bf16 v[68:71], v[152:155], v[204:207], v[68:71]
	v_mfma_f32_16x16x32_bf16 v[112:115], v[148:151], v[180:183], v[112:115]
	v_mfma_f32_16x16x32_bf16 v[104:107], v[156:159], v[180:183], v[104:107]
	v_mfma_f32_16x16x32_bf16 v[96:99], v[148:151], v[188:191], v[96:99]
	v_mfma_f32_16x16x32_bf16 v[92:95], v[156:159], v[188:191], v[92:95]
	s_setprio 2
	s_barrier
	v_mfma_f32_16x16x32_bf16 v[80:83], v[148:151], v[200:203], v[80:83]
	v_mfma_f32_16x16x32_bf16 v[84:87], v[156:159], v[200:203], v[84:87]
	v_mfma_f32_16x16x32_bf16 v[64:67], v[148:151], v[208:211], v[64:67]
	v_mfma_f32_16x16x32_bf16 v[68:71], v[156:159], v[208:211], v[68:71]
	s_setprio 0
	s_add_i32 s24, s54, s35
	v_lshl_add_u64 v[212:213], v[212:213], 0, s[16:17]
	s_mov_b32 m0, s24
	ds_read_b128 v[160:163], v199 offset:49152
	ds_read_b128 v[180:183], v199 offset:50176
	ds_read_b128 v[184:187], v199 offset:51200
	ds_read_b128 v[188:191], v199 offset:52224
	ds_read_b128 v[192:195], v199 offset:53248
	ds_read_b128 v[200:203], v199 offset:54272
	ds_read_b128 v[204:207], v199 offset:55296
	ds_read_b128 v[208:211], v199 offset:56320
	global_load_lds_dwordx4 v[212:213], off
	s_add_i32 m0, s24, 0x2000
	s_add_u32 s24, s26, 0xb0080
	v_lshl_add_u64 v[212:213], v[214:215], 0, s[16:17]
	s_addc_u32 s25, s27, 0
	s_add_i32 s26, s55, s35
	global_load_lds_dwordx4 v[212:213], off
	v_lshl_add_u64 v[212:213], s[24:25], 0, v[166:167]
	s_mov_b32 m0, s26
	s_nop 0
	global_load_lds_dwordx4 v[212:213], off
	v_lshl_add_u64 v[212:213], s[24:25], 0, v[170:171]
	s_add_i32 m0, s26, 0x2000
	s_nop 0
	global_load_lds_dwordx4 v[212:213], off
	v_lshl_add_u64 v[212:213], v[216:217], 0, s[16:17]
	s_mov_b32 m0, s41
	s_nop 0
	global_load_lds_dwordx4 v[212:213], off
	v_lshl_add_u64 v[212:213], v[218:219], 0, s[16:17]
	s_mov_b32 m0, s42
	s_nop 0
	global_load_lds_dwordx4 v[212:213], off
	s_waitcnt vmcnt(8)
	s_waitcnt lgkmcnt(0)
	s_barrier
	s_setprio 1
	s_waitcnt lgkmcnt(0)
	v_mfma_f32_16x16x32_bf16 v[56:59], v[128:131], v[160:163], v[56:59]
	v_mfma_f32_16x16x32_bf16 v[60:63], v[136:139], v[160:163], v[60:63]
	v_mfma_f32_16x16x32_bf16 v[40:43], v[128:131], v[184:187], v[40:43]
	v_mfma_f32_16x16x32_bf16 v[44:47], v[136:139], v[184:187], v[44:47]
	v_mfma_f32_16x16x32_bf16 v[24:27], v[128:131], v[192:195], v[24:27]
	v_mfma_f32_16x16x32_bf16 v[28:31], v[136:139], v[192:195], v[28:31]
	v_mfma_f32_16x16x32_bf16 v[8:11], v[128:131], v[204:207], v[8:11]
	v_mfma_f32_16x16x32_bf16 v[12:15], v[136:139], v[204:207], v[12:15]
	v_mfma_f32_16x16x32_bf16 v[56:59], v[132:135], v[180:183], v[56:59]
	v_mfma_f32_16x16x32_bf16 v[60:63], v[140:143], v[180:183], v[60:63]
	v_mfma_f32_16x16x32_bf16 v[40:43], v[132:135], v[188:191], v[40:43]
	v_mfma_f32_16x16x32_bf16 v[44:47], v[140:143], v[188:191], v[44:47]
	v_mfma_f32_16x16x32_bf16 v[24:27], v[132:135], v[200:203], v[24:27]
	v_mfma_f32_16x16x32_bf16 v[28:31], v[140:143], v[200:203], v[28:31]
	v_mfma_f32_16x16x32_bf16 v[8:11], v[132:135], v[208:211], v[8:11]
	v_mfma_f32_16x16x32_bf16 v[12:15], v[140:143], v[208:211], v[12:15]
	s_setprio 0
	s_setprio 1
	v_mfma_f32_16x16x32_bf16 v[48:51], v[144:147], v[160:163], v[48:51]
	v_mfma_f32_16x16x32_bf16 v[52:55], v[152:155], v[160:163], v[52:55]
	v_mfma_f32_16x16x32_bf16 v[32:35], v[144:147], v[184:187], v[32:35]
	v_mfma_f32_16x16x32_bf16 v[36:39], v[152:155], v[184:187], v[36:39]
	v_mfma_f32_16x16x32_bf16 v[16:19], v[144:147], v[192:195], v[16:19]
	v_mfma_f32_16x16x32_bf16 v[20:23], v[152:155], v[192:195], v[20:23]
	v_mfma_f32_16x16x32_bf16 v[0:3], v[144:147], v[204:207], v[0:3]
	v_mfma_f32_16x16x32_bf16 v[4:7], v[152:155], v[204:207], v[4:7]
	v_mfma_f32_16x16x32_bf16 v[48:51], v[148:151], v[180:183], v[48:51]
	v_mfma_f32_16x16x32_bf16 v[52:55], v[156:159], v[180:183], v[52:55]
	v_mfma_f32_16x16x32_bf16 v[32:35], v[148:151], v[188:191], v[32:35]
	v_mfma_f32_16x16x32_bf16 v[36:39], v[156:159], v[188:191], v[36:39]
	s_setprio 2
	s_barrier
	v_mfma_f32_16x16x32_bf16 v[16:19], v[148:151], v[200:203], v[16:19]
	v_mfma_f32_16x16x32_bf16 v[20:23], v[156:159], v[200:203], v[20:23]
	v_mfma_f32_16x16x32_bf16 v[0:3], v[148:151], v[208:211], v[0:3]
	v_mfma_f32_16x16x32_bf16 v[4:7], v[156:159], v[208:211], v[4:7]
	s_setprio 0
	s_add_i32 s53, s53, 2
	s_add_u32 s51, s51, 0x100
	s_addc_u32 s52, s52, 0
	s_cmp_gt_u32 s53, 41
	s_mov_b64 s[24:25], s[4:5]
